# scan: lazy decay (state kept divided by in-chunk decay product, rescaled per chunk; 2 FMA/elem update instead of 3; bonus product hoisted into stage 2)
# speedup vs baseline: 1.0331x; 1.0063x over previous
; DI int ltid() { int t = __builtin_amdgcn_workitem_id_x(); asm volatile("" : "+v"(t)); return t; }
; DI void scan_item(const Params& p, int l, bool ctx_out, int item, char* smem) {
;   const int dir = item & 1, h = (item >> 1) & 7, b = item >> 4;
;   const int tid = ltid(), lane = tid & 63, w = tid >> 6;
;   const int c = lane, tg = w;
;   const int kg = lane & 15, rg = lane >> 4;
;   const u16* __restrict__ Z = (const u16*)(p.ws + OFF_ZRW);
;   u16* YD = (u16*)(p.ws + OFF_QK) + (size_t)dir * NT * 512;
;   float* BON = (float*)(p.ws + OFF_BONUS) + (size_t)dir * NT * 8;
;   float* zs = (float*)smem;
;   float* ops = zs + TC * 3 * 64;
;   u16* zwb = (u16*)(ops + TC * 4 * 64);
;   u16* zab = zwb + 16 * 72;
;   const int hc = h * 64 + c;
;   const int cl = lane & 15, q4 = lane >> 4;
;   bf16x8 bw[2], ba[2];
;   {
;     const float* w2 = p.rwkv_w2 + (size_t)(l * 2 + dir) * 64 * 512 + h * 64 + 16 * w + cl;
;     const float* a2 = p.rwkv_a2 + (size_t)(l * 2 + dir) * 64 * 512 + h * 64 + 16 * w + cl;
; #pragma unroll
;     for (int s = 0; s < 2; ++s)
; #pragma unroll
;       for (int jj = 0; jj < 8; ++jj) {
;         const int j = s * 32 + q4 * 8 + jj;
;         bw[s][jj] = (short)f2bf(w2[j * 512]);
;         ba[s][jj] = (short)f2bf(a2[j * 512]);
;       }
;   }
;   const int hc2 = h * 64 + 16 * w + cl;
;   const float w0c = p.rwkv_w0[(l * 2 + dir) * 512 + hc2], a0c = p.rwkv_a0[(l * 2 + dir) * 512 + hc2];
;   const float kac = p.rwkv_k_a[l * 512 + hc2];
;   const float kkc = p.rwkv_k_k[l * 512 + hc];
;   f32x4 rk4;
; #pragma unroll
;   for (int j = 0; j < 4; ++j) rk4[j] = 0.5f * p.rwkv_r_k[l * 512 + h * 64 + 4 * kg + j];
;   const int gcol[5] = {hc, 512 + hc, 1024 + hc, 1536 + 64 * dir + c, 1664 + 64 * dir + c};
;   float muv[5];
; #pragma unroll
;   for (int g = 0; g < 5; ++g) muv[g] = p.rwkv_mu[l * RWB + gcol[g]];
.Lscan_item_loop:
	s_cmp_gt_i32 s24, 255
	s_cbranch_scc1 .Lscan_exit
	s_and_b32 s27, s24, 1
	s_bfe_u32 s28, s24, 0x30001
	s_lshr_b32 s29, s24, 4
	s_lshl_b32 s76, s26, 1
	s_add_i32 s76, s76, s27
	v_and_b32_e32 v224, 63, v196
	v_lshrrev_b32_e32 v225, 6, v196
	v_and_b32_e32 v241, 63, v196
	s_mov_b32 s0, 0xffff0000
	s_mov_b32 s1, -1
	s_mov_b32 s2, 0
	s_mov_b32 s3, -1
	s_lshl_b32 s54, s26, 9
	s_lshl_b32 s55, s28, 6
	s_add_i32 s54, s54, s55
	v_add_lshl_u32 v226, v224, s54, 2
	global_load_dword v191, v226, s[16:17]
	global_load_dword v192, v226, s[20:21]
	v_and_b32_e32 v227, 15, v224
	v_lshl_add_u32 v227, v225, 4, v227
	v_add_lshl_u32 v228, v227, s54, 2
	global_load_dword v190, v228, s[18:19]
	s_lshl_b32 s56, s76, 9
	s_add_i32 s56, s56, s55
	v_add_lshl_u32 v229, v227, s56, 2
	global_load_dword v188, v229, s[8:9]
	global_load_dword v189, v229, s[12:13]
	s_mul_i32 s57, s26, 1920
	s_add_i32 s58, s57, s55
	v_add_lshl_u32 v226, v224, s58, 2
	global_load_dword v193, v226, s[6:7]
	global_load_dword v194, v226, s[6:7] offset:2048
	s_lshl_b32 s59, s27, 6
	s_add_i32 s59, s59, s57
	s_addk_i32 s59, 0x600
	v_add_lshl_u32 v228, v224, s59, 2
	s_add_u32 s60, s6, 0x1000
	s_addc_u32 s61, s7, 0
	global_load_dword v195, v226, s[60:61]
	global_load_dword v207, v228, s[6:7]
	global_load_dword v208, v228, s[6:7] offset:512
	v_lshrrev_b32_e32 v226, 4, v224
	v_lshlrev_b32_e32 v226, 12, v226
	v_add_u32_e32 v226, v226, v227
	v_add_lshl_u32 v226, v226, s55, 2
	s_lshl_b32 s54, s76, 17
	s_add_u32 s60, s10, s54
	s_addc_u32 s61, s11, 0
	global_load_dword v22, v226, s[60:61]
	s_add_u32 s60, s60, 0x800
	s_addc_u32 s61, s61, 0
	global_load_dword v23, v226, s[60:61]
	s_add_u32 s60, s60, 0x800
	s_addc_u32 s61, s61, 0
	global_load_dword v24, v226, s[60:61]
	s_add_u32 s60, s60, 0x800
	s_addc_u32 s61, s61, 0
	global_load_dword v25, v226, s[60:61]
	s_add_u32 s60, s60, 0x800
	s_addc_u32 s61, s61, 0
	global_load_dword v26, v226, s[60:61]
	s_add_u32 s60, s60, 0x800
	s_addc_u32 s61, s61, 0
	global_load_dword v27, v226, s[60:61]
	s_add_u32 s60, s60, 0x800
	s_addc_u32 s61, s61, 0
	global_load_dword v28, v226, s[60:61]
	s_add_u32 s60, s60, 0x800
	s_addc_u32 s61, s61, 0
	global_load_dword v29, v226, s[60:61]
	s_add_u32 s60, s60, 0x800
	s_addc_u32 s61, s61, 0
	s_add_u32 s60, s60, 0xc000
	s_addc_u32 s61, s61, 0
	global_load_dword v30, v226, s[60:61]
	s_add_u32 s60, s60, 0x800
	s_addc_u32 s61, s61, 0
	global_load_dword v31, v226, s[60:61]
	s_add_u32 s60, s60, 0x800
	s_addc_u32 s61, s61, 0
	global_load_dword v32, v226, s[60:61]
	s_add_u32 s60, s60, 0x800
	s_addc_u32 s61, s61, 0
	global_load_dword v33, v226, s[60:61]
	s_add_u32 s60, s60, 0x800
	s_addc_u32 s61, s61, 0
	global_load_dword v34, v226, s[60:61]
	s_add_u32 s60, s60, 0x800
	s_addc_u32 s61, s61, 0
	global_load_dword v35, v226, s[60:61]
	s_add_u32 s60, s60, 0x800
	s_addc_u32 s61, s61, 0
	global_load_dword v36, v226, s[60:61]
	s_add_u32 s60, s60, 0x800
	s_addc_u32 s61, s61, 0
	global_load_dword v37, v226, s[60:61]
	s_add_u32 s60, s60, 0x800
	s_addc_u32 s61, s61, 0
	s_add_u32 s60, s14, s54
	s_addc_u32 s61, s15, 0
	global_load_dword v38, v226, s[60:61]
	s_add_u32 s60, s60, 0x800
	s_addc_u32 s61, s61, 0
	global_load_dword v39, v226, s[60:61]
	s_add_u32 s60, s60, 0x800
	s_addc_u32 s61, s61, 0
	global_load_dword v40, v226, s[60:61]
	s_add_u32 s60, s60, 0x800
	s_addc_u32 s61, s61, 0
	global_load_dword v41, v226, s[60:61]
	s_add_u32 s60, s60, 0x800
	s_addc_u32 s61, s61, 0
	global_load_dword v42, v226, s[60:61]
	s_add_u32 s60, s60, 0x800
	s_addc_u32 s61, s61, 0
	global_load_dword v43, v226, s[60:61]
	s_add_u32 s60, s60, 0x800
	s_addc_u32 s61, s61, 0
	global_load_dword v44, v226, s[60:61]
	s_add_u32 s60, s60, 0x800
	s_addc_u32 s61, s61, 0
	global_load_dword v45, v226, s[60:61]
	s_add_u32 s60, s60, 0x800
	s_addc_u32 s61, s61, 0
	s_add_u32 s60, s60, 0xc000
	s_addc_u32 s61, s61, 0
	global_load_dword v46, v226, s[60:61]
	s_add_u32 s60, s60, 0x800
	s_addc_u32 s61, s61, 0
	global_load_dword v47, v226, s[60:61]
	s_add_u32 s60, s60, 0x800
	s_addc_u32 s61, s61, 0
	global_load_dword v48, v226, s[60:61]
	s_add_u32 s60, s60, 0x800
	s_addc_u32 s61, s61, 0
	global_load_dword v49, v226, s[60:61]
	s_add_u32 s60, s60, 0x800
	s_addc_u32 s61, s61, 0
	global_load_dword v50, v226, s[60:61]
	s_add_u32 s60, s60, 0x800
	s_addc_u32 s61, s61, 0
	global_load_dword v51, v226, s[60:61]
	s_add_u32 s60, s60, 0x800
	s_addc_u32 s61, s61, 0
	global_load_dword v52, v226, s[60:61]
	s_add_u32 s60, s60, 0x800
	s_addc_u32 s61, s61, 0
	global_load_dword v53, v226, s[60:61]
	s_add_u32 s60, s60, 0x800
	s_addc_u32 s61, s61, 0
	s_waitcnt vmcnt(0)
; DI void scan_item(const Params& p, int l, bool ctx_out, int item, char* smem) {
;     ...
;   bf16x8 bw[2], ba[2];
;   {
;     const float* w2 = p.rwkv_w2 + (size_t)(l * 2 + dir) * 64 * 512 + h * 64 + 16 * w + cl;
;     const float* a2 = p.rwkv_a2 + (size_t)(l * 2 + dir) * 64 * 512 + h * 64 + 16 * w + cl;
; #pragma unroll
;     for (int s = 0; s < 2; ++s)
; #pragma unroll
;       for (int jj = 0; jj < 8; ++jj) {
;         const int j = s * 32 + q4 * 8 + jj;
;         bw[s][jj] = (short)f2bf(w2[j * 512]);
;         ba[s][jj] = (short)f2bf(a2[j * 512]);
;       }
;   }
;   const int hc2 = h * 64 + 16 * w + cl;
;   const float w0c = p.rwkv_w0[(l * 2 + dir) * 512 + hc2], a0c = p.rwkv_a0[(l * 2 + dir) * 512 + hc2];
;   const float kac = p.rwkv_k_a[l * 512 + hc2];
;   const float kkc = p.rwkv_k_k[l * 512 + hc];
;   f32x4 rk4;
; #pragma unroll
;   for (int j = 0; j < 4; ++j) rk4[j] = 0.5f * p.rwkv_r_k[l * 512 + h * 64 + 4 * kg + j];
;   const int gcol[5] = {hc, 512 + hc, 1024 + hc, 1536 + 64 * dir + c, 1664 + 64 * dir + c};
;   float muv[5];
; #pragma unroll
;   for (int g = 0; g < 5; ++g) muv[g] = p.rwkv_mu[l * RWB + gcol[g]];
;   float S[4][4];
; #pragma unroll
;   for (int a = 0; a < 4; ++a)
; #pragma unroll
;     for (int j = 0; j < 4; ++j) S[a][j] = 0.f;
;   __syncthreads();
;   u16 raw[4][5][2];
;   const int NCH = 256 / TC + 2048 / TC;
;     ...
;   ISSUE_LOADS(0)
	v_cvt_pk_bf16_f32 v170, v22, v23
	v_cvt_pk_bf16_f32 v171, v24, v25
	v_cvt_pk_bf16_f32 v172, v26, v27
	v_cvt_pk_bf16_f32 v173, v28, v29
	v_cvt_pk_bf16_f32 v174, v30, v31
	v_cvt_pk_bf16_f32 v175, v32, v33
	v_cvt_pk_bf16_f32 v176, v34, v35
	v_cvt_pk_bf16_f32 v177, v36, v37
	v_cvt_pk_bf16_f32 v180, v38, v39
	v_cvt_pk_bf16_f32 v181, v40, v41
	v_cvt_pk_bf16_f32 v182, v42, v43
	v_cvt_pk_bf16_f32 v183, v44, v45
	v_cvt_pk_bf16_f32 v184, v46, v47
	v_cvt_pk_bf16_f32 v185, v48, v49
	v_cvt_pk_bf16_f32 v186, v50, v51
	v_cvt_pk_bf16_f32 v187, v52, v53
	v_mul_f32_e32 v192, 0.5, v192
	s_lshl_b32 s54, s28, 7
	v_lshl_add_u32 v209, v224, 1, s54
	s_lshl_b32 s54, s27, 7
	s_addk_i32 s54, 0xc00
	v_lshl_add_u32 v210, v224, 1, s54
	v_and_b32_e32 v226, 3, v224
	v_mov_b32_e32 v213, 241920
	v_mov_b32_e32 v214, 241920
	v_mov_b32_e32 v227, 249600
	v_cmp_eq_u32_e32 vcc, 1, v226
	s_nop 1
	v_cndmask_b32_e32 v213, v213, v227, vcc
	v_cndmask_b32_e32 v214, v214, v227, vcc
	v_cmp_eq_u32_e32 vcc, 3, v226
	s_nop 1
	v_cndmask_b32_e32 v214, v214, v227, vcc
	v_mov_b32_e32 v227, 491520
	s_nop 0
	v_cndmask_b32_e32 v213, v213, v227, vcc
	v_cmp_eq_u32_e32 vcc, 2, v226
	s_nop 1
	v_cndmask_b32_e32 v213, v213, v240, vcc
	s_mul_i32 s54, s30, 6144
	v_lshl_add_u32 v215, v224, 2, s54
	s_mul_i32 s54, s30, 576
	s_add_i32 s54, s54, 49152
	v_lshl_add_u32 v216, v224, 1, s54
	v_and_b32_e32 v226, 15, v224
	v_lshrrev_b32_e32 v227, 4, v224
	s_lshl_b32 s54, s30, 6
	v_lshl_add_u32 v217, v226, 2, s54
	v_mul_u32_u24_e32 v228, 6144, v227
	v_add_u32_e32 v217, v217, v228
	v_mul_u32_u24_e32 v228, 144, v226
	v_lshl_add_u32 v218, v227, 4, v228
	v_add_u32_e32 v218, 49152, v218
	v_and_b32_e32 v226, 7, v224
	v_lshlrev_b32_e32 v219, 5, v226
	v_lshrrev_b32_e32 v227, 3, v224
	s_lshl_b32 s54, s30, 6
	s_add_i32 s55, s54, 1280
	v_lshl_add_u32 v220, v227, 3, s55
	s_lshl_b32 s54, s30, 5
	s_add_i32 s55, s54, 53760
	v_lshl_add_u32 v221, v227, 2, s55
	v_lshrrev_b32_e32 v226, 2, v224
	v_and_b32_e32 v227, 3, v224
	v_lshlrev_b32_e32 v228, 7, v226
	v_lshl_add_u32 v228, v227, 3, v228
	v_add_u32_e32 v222, s55, v228
	v_sub_u32_e32 v228, 15, v226
	s_cmp_eq_u32 s27, 1
	s_cselect_b64 vcc, -1, 0
	v_cndmask_b32_e32 v228, v226, v228, vcc
	v_lshlrev_b32_e32 v228, 10, v228
	v_lshl_add_u32 v223, v227, 3, v228
	s_mul_i32 s54, s27, 0x2400000
	s_lshl_b32 s55, s28, 7
	s_add_i32 s54, s54, s55
	s_lshl_b32 s55, s30, 5
	s_add_i32 s54, s54, s55
	s_add_u32 s36, s22, 0x6b60000
	s_addc_u32 s37, s23, 0
	s_add_u32 s36, s36, s54
	s_addc_u32 s37, s37, 0
	s_mul_i32 s54, s27, 0x120000
	s_lshl_b32 s55, s28, 2
	s_add_i32 s54, s54, s55
	s_add_u32 s38, s22, 0x1db2c000
	s_addc_u32 s39, s23, 0
	s_add_u32 s38, s38, s54
	s_addc_u32 s39, s39, 0
	v_mov_b32_e32 v6, 0
	v_mov_b32_e32 v7, 0
	v_mov_b32_e32 v8, 0
	v_mov_b32_e32 v9, 0
	v_mov_b32_e32 v10, 0
	v_mov_b32_e32 v11, 0
	v_mov_b32_e32 v12, 0
	v_mov_b32_e32 v13, 0
	v_mov_b32_e32 v14, 0
	v_mov_b32_e32 v15, 0
	v_mov_b32_e32 v16, 0
	v_mov_b32_e32 v17, 0
	v_mov_b32_e32 v18, 0
	v_mov_b32_e32 v19, 0
	v_mov_b32_e32 v20, 0
	v_mov_b32_e32 v21, 0
	s_mov_b32 s31, 0
	s_mov_b32 s77, 0
	s_waitcnt vmcnt(0) lgkmcnt(0)
	s_barrier
	s_mov_b32 s62, 0
	s_lshl_b32 s54, s29, 8
	s_add_i32 s54, s54, 32768
	s_lshl_b32 s55, s29, 11
	s_lshl_b32 s56, s62, 4
	s_add_i32 s57, s56, -256
	s_movk_i32 s58, 256
	s_movk_i32 s59, 2048
	s_cmp_lt_u32 s62, 16
	s_cselect_b32 s72, s58, s59
	s_cselect_b32 s75, 1, 0
	s_cselect_b32 s73, s54, s55
	s_cselect_b32 s74, s56, s57
	s_cmp_eq_u32 s75, 1
	s_cselect_b64 vcc, -1, 0
	v_cndmask_b32_e32 v252, v213, v214, vcc
	v_add_u32_e32 v211, v209, v252
	v_add_u32_e32 v212, v210, v252
	s_lshl_b32 s54, s30, 2
	s_add_i32 s54, s54, s74
	s_sub_i32 s55, s72, s54
	s_add_i32 s55, s55, -1
	s_cmp_eq_u32 s27, 1
	s_cselect_b32 s54, s55, s54
	s_add_i32 s55, s54, s73
	s_mul_i32 s55, s55, 3840
	s_add_u32 s64, s32, s55
	s_addc_u32 s65, s33, 0
	s_add_u32 s66, s34, s55
	s_addc_u32 s67, s35, 0
	s_and_b32 s56, s54, 63
	s_lshr_b32 s57, s54, 6
	s_cmp_eq_u32 s75, 1
	s_cselect_b32 s56, s54, s56
	s_cselect_b32 s58, 255, 63
	s_cselect_b32 s59, s54, s57
	s_cselect_b32 s60, 255, 31
	s_cselect_b32 s61, s54, s57
	s_cselect_b32 s57, s54, s56
	s_cmp_gt_u32 s56, 0
	s_cselect_b64 s[68:69], s[40:41], 0
	s_cmp_lt_u32 s57, s58
	s_cselect_b64 s[54:55], s[42:43], 0
	s_or_b64 s[68:69], s[68:69], s[54:55]
	s_cmp_gt_u32 s59, 0
	s_cselect_b64 s[54:55], s[44:45], 0
	s_or_b64 s[68:69], s[68:69], s[54:55]
	s_cmp_lt_u32 s61, s60
	s_cselect_b64 s[54:55], s[46:47], 0
	s_or_b64 s[68:69], s[68:69], s[54:55]
	v_mov_b32_e32 v131, 0
	v_mov_b32_e32 v133, 0
	v_mov_b32_e32 v135, 0
	v_mov_b32_e32 v137, 0
	v_mov_b32_e32 v139, 0
	global_load_ushort v130, v209, s[64:65]
	global_load_ushort v132, v209, s[64:65] offset:1024
	global_load_ushort v134, v209, s[64:65] offset:2048
	global_load_ushort v136, v210, s[64:65]
	global_load_ushort v138, v210, s[64:65] offset:256
	s_mov_b64 exec, s[68:69]
	global_load_ushort v131, v211, s[66:67]
	global_load_ushort v133, v211, s[66:67] offset:1024
	global_load_ushort v135, v211, s[66:67] offset:2048
	global_load_ushort v137, v212, s[66:67]
	global_load_ushort v139, v212, s[66:67] offset:256
	s_mov_b64 exec, -1
	s_lshl_b32 s54, s30, 2
	s_add_i32 s54, s54, s74
	s_add_i32 s54, s54, 1
	s_sub_i32 s55, s72, s54
	s_add_i32 s55, s55, -1
	s_cmp_eq_u32 s27, 1
	s_cselect_b32 s54, s55, s54
	s_add_i32 s55, s54, s73
	s_mul_i32 s55, s55, 3840
	s_add_u32 s64, s32, s55
	s_addc_u32 s65, s33, 0
	s_add_u32 s66, s34, s55
	s_addc_u32 s67, s35, 0
	s_and_b32 s56, s54, 63
	s_lshr_b32 s57, s54, 6
	s_cmp_eq_u32 s75, 1
	s_cselect_b32 s56, s54, s56
	s_cselect_b32 s58, 255, 63
	s_cselect_b32 s59, s54, s57
	s_cselect_b32 s60, 255, 31
	s_cselect_b32 s61, s54, s57
; DI void scan_item(const Params& p, int l, bool ctx_out, int item, char* smem) {
;     ...
;   ISSUE_LOADS(0)
; #pragma unroll 1
;   for (int ci = 0; ci < NCH; ++ci) {
;     CHUNK_INFO(ci, n, rbase, c0)
	s_cselect_b32 s57, s54, s56
	s_cmp_gt_u32 s56, 0
	s_cselect_b64 s[68:69], s[40:41], 0
	s_cmp_lt_u32 s57, s58
	s_cselect_b64 s[54:55], s[42:43], 0
	s_or_b64 s[68:69], s[68:69], s[54:55]
	s_cmp_gt_u32 s59, 0
	s_cselect_b64 s[54:55], s[44:45], 0
	s_or_b64 s[68:69], s[68:69], s[54:55]
	s_cmp_lt_u32 s61, s60
	s_cselect_b64 s[54:55], s[46:47], 0
	s_or_b64 s[68:69], s[68:69], s[54:55]
	v_mov_b32_e32 v141, 0
	v_mov_b32_e32 v143, 0
	v_mov_b32_e32 v145, 0
	v_mov_b32_e32 v147, 0
	v_mov_b32_e32 v149, 0
	global_load_ushort v140, v209, s[64:65]
	global_load_ushort v142, v209, s[64:65] offset:1024
	global_load_ushort v144, v209, s[64:65] offset:2048
	global_load_ushort v146, v210, s[64:65]
	global_load_ushort v148, v210, s[64:65] offset:256
	s_mov_b64 exec, s[68:69]
	global_load_ushort v141, v211, s[66:67]
	global_load_ushort v143, v211, s[66:67] offset:1024
	global_load_ushort v145, v211, s[66:67] offset:2048
	global_load_ushort v147, v212, s[66:67]
	global_load_ushort v149, v212, s[66:67] offset:256
	s_mov_b64 exec, -1
	s_lshl_b32 s54, s30, 2
	s_add_i32 s54, s54, s74
	s_add_i32 s54, s54, 2
	s_sub_i32 s55, s72, s54
	s_add_i32 s55, s55, -1
	s_cmp_eq_u32 s27, 1
	s_cselect_b32 s54, s55, s54
	s_add_i32 s55, s54, s73
	s_mul_i32 s55, s55, 3840
	s_add_u32 s64, s32, s55
	s_addc_u32 s65, s33, 0
	s_add_u32 s66, s34, s55
	s_addc_u32 s67, s35, 0
	s_and_b32 s56, s54, 63
	s_lshr_b32 s57, s54, 6
	s_cmp_eq_u32 s75, 1
	s_cselect_b32 s56, s54, s56
	s_cselect_b32 s58, 255, 63
	s_cselect_b32 s59, s54, s57
	s_cselect_b32 s60, 255, 31
	s_cselect_b32 s61, s54, s57
	s_cselect_b32 s57, s54, s56
	s_cmp_gt_u32 s56, 0
	s_cselect_b64 s[68:69], s[40:41], 0
	s_cmp_lt_u32 s57, s58
	s_cselect_b64 s[54:55], s[42:43], 0
	s_or_b64 s[68:69], s[68:69], s[54:55]
	s_cmp_gt_u32 s59, 0
	s_cselect_b64 s[54:55], s[44:45], 0
	s_or_b64 s[68:69], s[68:69], s[54:55]
	s_cmp_lt_u32 s61, s60
	s_cselect_b64 s[54:55], s[46:47], 0
	s_or_b64 s[68:69], s[68:69], s[54:55]
	v_mov_b32_e32 v151, 0
	v_mov_b32_e32 v153, 0
	v_mov_b32_e32 v155, 0
	v_mov_b32_e32 v157, 0
	v_mov_b32_e32 v159, 0
	global_load_ushort v150, v209, s[64:65]
	global_load_ushort v152, v209, s[64:65] offset:1024
	global_load_ushort v154, v209, s[64:65] offset:2048
	global_load_ushort v156, v210, s[64:65]
	global_load_ushort v158, v210, s[64:65] offset:256
	s_mov_b64 exec, s[68:69]
	global_load_ushort v151, v211, s[66:67]
	global_load_ushort v153, v211, s[66:67] offset:1024
	global_load_ushort v155, v211, s[66:67] offset:2048
	global_load_ushort v157, v212, s[66:67]
	global_load_ushort v159, v212, s[66:67] offset:256
	s_mov_b64 exec, -1
	s_lshl_b32 s54, s30, 2
	s_add_i32 s54, s54, s74
	s_add_i32 s54, s54, 3
	s_sub_i32 s55, s72, s54
	s_add_i32 s55, s55, -1
	s_cmp_eq_u32 s27, 1
	s_cselect_b32 s54, s55, s54
	s_add_i32 s55, s54, s73
	s_mul_i32 s55, s55, 3840
	s_add_u32 s64, s32, s55
	s_addc_u32 s65, s33, 0
	s_add_u32 s66, s34, s55
	s_addc_u32 s67, s35, 0
	s_and_b32 s56, s54, 63
	s_lshr_b32 s57, s54, 6
	s_cmp_eq_u32 s75, 1
	s_cselect_b32 s56, s54, s56
	s_cselect_b32 s58, 255, 63
	s_cselect_b32 s59, s54, s57
	s_cselect_b32 s60, 255, 31
	s_cselect_b32 s61, s54, s57
	s_cselect_b32 s57, s54, s56
	s_cmp_gt_u32 s56, 0
	s_cselect_b64 s[68:69], s[40:41], 0
	s_cmp_lt_u32 s57, s58
	s_cselect_b64 s[54:55], s[42:43], 0
	s_or_b64 s[68:69], s[68:69], s[54:55]
	s_cmp_gt_u32 s59, 0
	s_cselect_b64 s[54:55], s[44:45], 0
	s_or_b64 s[68:69], s[68:69], s[54:55]
	s_cmp_lt_u32 s61, s60
	s_cselect_b64 s[54:55], s[46:47], 0
	s_or_b64 s[68:69], s[68:69], s[54:55]
	v_mov_b32_e32 v161, 0
	v_mov_b32_e32 v163, 0
	v_mov_b32_e32 v165, 0
	v_mov_b32_e32 v167, 0
	v_mov_b32_e32 v169, 0
	global_load_ushort v160, v209, s[64:65]
	global_load_ushort v162, v209, s[64:65] offset:1024
	global_load_ushort v164, v209, s[64:65] offset:2048
	global_load_ushort v166, v210, s[64:65]
	global_load_ushort v168, v210, s[64:65] offset:256
	s_mov_b64 exec, s[68:69]
	global_load_ushort v161, v211, s[66:67]
	global_load_ushort v163, v211, s[66:67] offset:1024
	global_load_ushort v165, v211, s[66:67] offset:2048
	global_load_ushort v167, v212, s[66:67]
	global_load_ushort v169, v212, s[66:67] offset:256
	s_mov_b64 exec, -1
.Lscan_chunk_loop:
	s_lshl_b32 s54, s29, 8
	s_add_i32 s54, s54, 32768
	s_lshl_b32 s55, s29, 11
	s_lshl_b32 s56, s31, 4
	s_add_i32 s57, s56, -256
	s_movk_i32 s58, 256
	s_movk_i32 s59, 2048
	s_cmp_lt_u32 s31, 16
	s_cselect_b32 s48, s58, s59
	s_cselect_b32 s49, s54, s55
	s_cselect_b32 s50, s56, s57
	s_cselect_b32 s51, s52, 1
	v_add_u32_e32 v248, s77, v215
	s_waitcnt vmcnt(0)
; DI float bf2f(u16 v) { return __uint_as_float(((unsigned)v) << 16); }
; DI float tanhf_(float x) { return 1.f - 2.f * frcp(__expf(2.f * x) + 1.f); }
; DI void scan_item(const Params& p, int l, bool ctx_out, int item, char* smem) {
;     ...
; #pragma unroll
;     for (int q = 0; q < 4; ++q) {
;       const int i = tg * 4 + q;
;       float zv[5];
; #pragma unroll
;       for (int g = 0; g < 5; ++g) {
;         const float v0 = bf2f(raw[q][g][0]), v1 = bf2f(raw[q][g][1]);
;         zv[g] = v0 + muv[g] * (v1 - v0);
;       }
;       zs[(i * 3 + 0) * 64 + c] = zv[0];
;       zs[(i * 3 + 1) * 64 + c] = zv[1];
;       zs[(i * 3 + 2) * 64 + c] = zv[2];
;       zwb[i * 72 + c] = f2bf(tanhf_(zv[3]));
;       zab[i * 72 + c] = f2bf(zv[4]);
;       const float kkr = zv[1] * kkc;
;       const float ss = wave_sum_dpp(kkr * kkr);
;       ops[(i * 4 + 1) * 64 + c] = kkr * rsqrtf(ss + 1e-12f);
;     }
	v_lshlrev_b32_e32 v130, 16, v130
	v_lshlrev_b32_e32 v131, 16, v131
	v_lshlrev_b32_e32 v132, 16, v132
	v_lshlrev_b32_e32 v133, 16, v133
	v_lshlrev_b32_e32 v134, 16, v134
	v_lshlrev_b32_e32 v135, 16, v135
	v_lshlrev_b32_e32 v136, 16, v136
	v_lshlrev_b32_e32 v137, 16, v137
	v_lshlrev_b32_e32 v138, 16, v138
	v_lshlrev_b32_e32 v139, 16, v139
	v_sub_f32_e32 v131, v131, v130
	v_sub_f32_e32 v133, v133, v132
	v_sub_f32_e32 v135, v135, v134
	v_sub_f32_e32 v137, v137, v136
	v_sub_f32_e32 v139, v139, v138
	v_fma_f32 v106, v193, v131, v130
	v_fma_f32 v107, v194, v133, v132
	v_fma_f32 v108, v195, v135, v134
	v_fma_f32 v109, v207, v137, v136
	v_fma_f32 v224, v208, v139, v138
	ds_write_b32 v248, v106 offset:1024
	ds_write_b32 v248, v107 offset:768
	ds_write_b32 v248, v108 offset:1280
	v_mul_f32_e32 v228, v107, v191
	v_mul_f32_e32 v232, v228, v228
	v_lshlrev_b32_e32 v140, 16, v140
	v_lshlrev_b32_e32 v141, 16, v141
	v_lshlrev_b32_e32 v142, 16, v142
	v_lshlrev_b32_e32 v143, 16, v143
	v_lshlrev_b32_e32 v144, 16, v144
	v_lshlrev_b32_e32 v145, 16, v145
	v_lshlrev_b32_e32 v146, 16, v146
	v_lshlrev_b32_e32 v147, 16, v147
	v_lshlrev_b32_e32 v148, 16, v148
	v_lshlrev_b32_e32 v149, 16, v149
	v_sub_f32_e32 v141, v141, v140
	v_sub_f32_e32 v143, v143, v142
	v_sub_f32_e32 v145, v145, v144
	v_sub_f32_e32 v147, v147, v146
	v_sub_f32_e32 v149, v149, v148
	v_fma_f32 v110, v193, v141, v140
	v_fma_f32 v111, v194, v143, v142
	v_fma_f32 v112, v195, v145, v144
	v_fma_f32 v113, v207, v147, v146
	v_fma_f32 v225, v208, v149, v148
	ds_write_b32 v248, v110 offset:2560
	ds_write_b32 v248, v111 offset:2304
	ds_write_b32 v248, v112 offset:2816
	v_mul_f32_e32 v229, v111, v191
	v_mul_f32_e32 v233, v229, v229
	v_lshlrev_b32_e32 v150, 16, v150
	v_lshlrev_b32_e32 v151, 16, v151
	v_lshlrev_b32_e32 v152, 16, v152
	v_lshlrev_b32_e32 v153, 16, v153
	v_lshlrev_b32_e32 v154, 16, v154
	v_lshlrev_b32_e32 v155, 16, v155
	v_lshlrev_b32_e32 v156, 16, v156
	v_lshlrev_b32_e32 v157, 16, v157
	v_lshlrev_b32_e32 v158, 16, v158
	v_lshlrev_b32_e32 v159, 16, v159
	v_sub_f32_e32 v151, v151, v150
	v_sub_f32_e32 v153, v153, v152
	v_sub_f32_e32 v155, v155, v154
	v_sub_f32_e32 v157, v157, v156
	v_sub_f32_e32 v159, v159, v158
	v_fma_f32 v114, v193, v151, v150
	v_fma_f32 v115, v194, v153, v152
	v_fma_f32 v116, v195, v155, v154
	v_fma_f32 v117, v207, v157, v156
	v_fma_f32 v226, v208, v159, v158
	ds_write_b32 v248, v114 offset:4096
	ds_write_b32 v248, v115 offset:3840
	ds_write_b32 v248, v116 offset:4352
	v_mul_f32_e32 v230, v115, v191
	v_mul_f32_e32 v234, v230, v230
	v_lshlrev_b32_e32 v160, 16, v160
	v_lshlrev_b32_e32 v161, 16, v161
	v_lshlrev_b32_e32 v162, 16, v162
	v_lshlrev_b32_e32 v163, 16, v163
	v_lshlrev_b32_e32 v164, 16, v164
	v_lshlrev_b32_e32 v165, 16, v165
	v_lshlrev_b32_e32 v166, 16, v166
	v_lshlrev_b32_e32 v167, 16, v167
	v_lshlrev_b32_e32 v168, 16, v168
	v_lshlrev_b32_e32 v169, 16, v169
	v_sub_f32_e32 v161, v161, v160
	v_sub_f32_e32 v163, v163, v162
	v_sub_f32_e32 v165, v165, v164
	v_sub_f32_e32 v167, v167, v166
	v_sub_f32_e32 v169, v169, v168
	v_fma_f32 v118, v193, v161, v160
	v_fma_f32 v119, v194, v163, v162
	v_fma_f32 v120, v195, v165, v164
	v_fma_f32 v121, v207, v167, v166
	v_fma_f32 v227, v208, v169, v168
	ds_write_b32 v248, v118 offset:5632
	ds_write_b32 v248, v119 offset:5376
	ds_write_b32 v248, v120 offset:5888
	v_mul_f32_e32 v231, v119, v191
	v_mul_f32_e32 v235, v231, v231
	v_mul_f32_e32 v109, 0x4038aa3b, v109
	v_mul_f32_e32 v113, 0x4038aa3b, v113
	v_mul_f32_e32 v117, 0x4038aa3b, v117
	v_mul_f32_e32 v121, 0x4038aa3b, v121
	v_exp_f32_e32 v109, v109
	v_exp_f32_e32 v113, v113
	v_exp_f32_e32 v117, v117
	v_exp_f32_e32 v121, v121
	s_nop 0
	v_add_f32_e32 v109, 1.0, v109
	v_add_f32_e32 v113, 1.0, v113
	v_add_f32_e32 v117, 1.0, v117
	v_add_f32_e32 v121, 1.0, v121
	v_rcp_f32_e32 v109, v109
	v_rcp_f32_e32 v113, v113
	v_rcp_f32_e32 v117, v117
	v_rcp_f32_e32 v121, v121
	s_nop 0
	v_fma_f32 v109, v109, -2.0, 1.0
	v_fma_f32 v113, v113, -2.0, 1.0
	v_fma_f32 v117, v117, -2.0, 1.0
	v_fma_f32 v121, v121, -2.0, 1.0
	v_cvt_pk_bf16_f32 v109, v109, v224
	v_cvt_pk_bf16_f32 v113, v113, v225
	v_cvt_pk_bf16_f32 v117, v117, v226
	v_cvt_pk_bf16_f32 v121, v121, v227
	ds_write_b16 v216, v109 offset:0
	ds_write_b16_d16_hi v216, v109 offset:2304
	ds_write_b16 v216, v113 offset:144
	ds_write_b16_d16_hi v216, v113 offset:2448
	ds_write_b16 v216, v117 offset:288
	ds_write_b16_d16_hi v216, v117 offset:2592
	ds_write_b16 v216, v121 offset:432
	ds_write_b16_d16_hi v216, v121 offset:2736
	v_add_f32_dpp v232, v232, v232 quad_perm:[1,0,3,2] row_mask:0xf bank_mask:0xf bound_ctrl:1
	v_add_f32_dpp v233, v233, v233 quad_perm:[1,0,3,2] row_mask:0xf bank_mask:0xf bound_ctrl:1
	v_add_f32_dpp v234, v234, v234 quad_perm:[1,0,3,2] row_mask:0xf bank_mask:0xf bound_ctrl:1
	v_add_f32_dpp v235, v235, v235 quad_perm:[1,0,3,2] row_mask:0xf bank_mask:0xf bound_ctrl:1
	v_add_f32_dpp v232, v232, v232 quad_perm:[2,3,0,1] row_mask:0xf bank_mask:0xf bound_ctrl:1
	v_add_f32_dpp v233, v233, v233 quad_perm:[2,3,0,1] row_mask:0xf bank_mask:0xf bound_ctrl:1
	v_add_f32_dpp v234, v234, v234 quad_perm:[2,3,0,1] row_mask:0xf bank_mask:0xf bound_ctrl:1
	v_add_f32_dpp v235, v235, v235 quad_perm:[2,3,0,1] row_mask:0xf bank_mask:0xf bound_ctrl:1
	v_add_f32_dpp v232, v232, v232 row_half_mirror row_mask:0xf bank_mask:0xf bound_ctrl:1
	v_add_f32_dpp v233, v233, v233 row_half_mirror row_mask:0xf bank_mask:0xf bound_ctrl:1
	v_add_f32_dpp v234, v234, v234 row_half_mirror row_mask:0xf bank_mask:0xf bound_ctrl:1
	v_add_f32_dpp v235, v235, v235 row_half_mirror row_mask:0xf bank_mask:0xf bound_ctrl:1
	v_add_f32_dpp v232, v232, v232 row_mirror row_mask:0xf bank_mask:0xf bound_ctrl:1
; DI float sigmoidf_(float x) { return frcp(1.f + __expf(-x)); }
; #define MFMA16(a, b, c) __builtin_amdgcn_mfma_f32_16x16x32_bf16((a), (b), (c), 0, 0, 0)
; DI void scan_item(const Params& p, int l, bool ctx_out, int item, char* smem) {
;     ...
;       const float kkr = zv[1] * kkc;
;       const float ss = wave_sum_dpp(kkr * kkr);
;       ops[(i * 4 + 1) * 64 + c] = kkr * rsqrtf(ss + 1e-12f);
;     }
;     __syncthreads();
;     {
;       f32x4_t accw = {0.f, 0.f, 0.f, 0.f}, acca = {0.f, 0.f, 0.f, 0.f};
; #pragma unroll
;       for (int s = 0; s < 2; ++s) {
;         const bf16x8 aw = *(const bf16x8*)(zwb + cl * 72 + s * 32 + q4 * 8);
;         const bf16x8 aa = *(const bf16x8*)(zab + cl * 72 + s * 32 + q4 * 8);
;         accw = MFMA16(aw, bw[s], accw);
;         acca = MFMA16(aa, ba[s], acca);
;       }
;       const int ch = 16 * w + cl;
; #pragma unroll
;       for (int rr = 0; rr < 4; ++rr) {
;         const int i = 4 * q4 + rr;
;         const float wl = accw[rr] + w0c, al = acca[rr] + a0c;
;         const float sp = __logf(1.f + __expf(-wl));
;         const float dec = __expf(-__expf(-sp - 0.5f));
;         const float av = sigmoidf_(al);
;         const float zk = zs[(i * 3 + 1) * 64 + ch];
;         const float kkn = ops[(i * 4 + 1) * 64 + ch];
;         ops[(i * 4 + 0) * 64 + ch] = dec;
;         ops[(i * 4 + 2) * 64 + ch] = kkn * av;
;         ops[(i * 4 + 3) * 64 + ch] = zk * (1.f + (av - 1.f) * kac);
;       }
	v_add_f32_dpp v233, v233, v233 row_mirror row_mask:0xf bank_mask:0xf bound_ctrl:1
	v_add_f32_dpp v234, v234, v234 row_mirror row_mask:0xf bank_mask:0xf bound_ctrl:1
	v_add_f32_dpp v235, v235, v235 row_mirror row_mask:0xf bank_mask:0xf bound_ctrl:1
	s_nop 0
	v_readlane_b32 s54, v232, 0
	v_readlane_b32 s55, v232, 16
	v_readlane_b32 s56, v232, 32
	v_readlane_b32 s57, v232, 48
	s_nop 1
	v_mov_b32_e32 v232, s54
	v_add_f32_e32 v232, s55, v232
	v_add_f32_e32 v232, s56, v232
	v_add_f32_e32 v232, s57, v232
	v_readlane_b32 s54, v233, 0
	v_readlane_b32 s55, v233, 16
	v_readlane_b32 s56, v233, 32
	v_readlane_b32 s57, v233, 48
	s_nop 1
	v_mov_b32_e32 v233, s54
	v_add_f32_e32 v233, s55, v233
	v_add_f32_e32 v233, s56, v233
	v_add_f32_e32 v233, s57, v233
	v_readlane_b32 s54, v234, 0
	v_readlane_b32 s55, v234, 16
	v_readlane_b32 s56, v234, 32
	v_readlane_b32 s57, v234, 48
	s_nop 1
	v_mov_b32_e32 v234, s54
	v_add_f32_e32 v234, s55, v234
	v_add_f32_e32 v234, s56, v234
	v_add_f32_e32 v234, s57, v234
	v_readlane_b32 s54, v235, 0
	v_readlane_b32 s55, v235, 16
	v_readlane_b32 s56, v235, 32
	v_readlane_b32 s57, v235, 48
	s_nop 1
	v_mov_b32_e32 v235, s54
	v_add_f32_e32 v235, s55, v235
	v_add_f32_e32 v235, s56, v235
	v_add_f32_e32 v235, s57, v235
	v_add_f32_e32 v232, 0x2b8cbccc, v232
	v_add_f32_e32 v233, 0x2b8cbccc, v233
	v_add_f32_e32 v234, 0x2b8cbccc, v234
	v_add_f32_e32 v235, 0x2b8cbccc, v235
	v_rsq_f32_e32 v232, v232
	v_rsq_f32_e32 v233, v233
	v_rsq_f32_e32 v234, v234
	v_rsq_f32_e32 v235, v235
	s_nop 0
	v_mul_f32_e32 v228, v228, v232
	v_mul_f32_e32 v229, v229, v233
	v_mul_f32_e32 v230, v230, v234
	v_mul_f32_e32 v231, v231, v235
	ds_write_b32 v248, v228 offset:256
	ds_write_b32 v248, v229 offset:1792
	ds_write_b32 v248, v230 offset:3328
	ds_write_b32 v248, v231 offset:4864
	s_waitcnt lgkmcnt(0)
	s_barrier
	v_add_u32_e32 v248, s77, v217
	ds_read_b128 v[114:117], v218
	ds_read_b128 v[118:121], v218 offset:64
	ds_read_b128 v[106:109], v218 offset:2304
	ds_read_b128 v[110:113], v218 offset:2368
	ds_read_b32 v224, v248 offset:768
	ds_read_b32 v236, v248 offset:256
	ds_read_b32 v225, v248 offset:2304
	ds_read_b32 v237, v248 offset:1792
	ds_read_b32 v226, v248 offset:3840
	ds_read_b32 v238, v248 offset:3328
	ds_read_b32 v227, v248 offset:5376
	ds_read_b32 v239, v248 offset:4864
	ds_read_b32 v130, v248 offset:1024
	ds_read_b32 v131, v248 offset:2560
	ds_read_b32 v132, v248 offset:4096
	ds_read_b32 v133, v248 offset:5632
	s_waitcnt lgkmcnt(14)
	v_mfma_f32_16x16x32_bf16 v[228:231], v[114:117], v[170:173], 0
	s_waitcnt lgkmcnt(12)
	v_mfma_f32_16x16x32_bf16 v[232:235], v[106:109], v[180:183], 0
	v_mfma_f32_16x16x32_bf16 v[228:231], v[118:121], v[174:177], v[228:231]
	v_mfma_f32_16x16x32_bf16 v[232:235], v[110:113], v[184:187], v[232:235]
	s_nop 7
	s_nop 1
	v_add_f32_e32 v228, v228, v188
	v_add_f32_e32 v229, v229, v188
	v_add_f32_e32 v230, v230, v188
	v_add_f32_e32 v231, v231, v188
	v_add_f32_e32 v232, v232, v189
	v_add_f32_e32 v233, v233, v189
	v_add_f32_e32 v234, v234, v189
	v_add_f32_e32 v235, v235, v189
	v_mul_f32_e32 v228, 0xbfb8aa3b, v228
	v_mul_f32_e32 v229, 0xbfb8aa3b, v229
	v_mul_f32_e32 v230, 0xbfb8aa3b, v230
	v_mul_f32_e32 v231, 0xbfb8aa3b, v231
	v_mul_f32_e32 v232, 0xbfb8aa3b, v232
	v_mul_f32_e32 v233, 0xbfb8aa3b, v233
	v_mul_f32_e32 v234, 0xbfb8aa3b, v234
	v_mul_f32_e32 v235, 0xbfb8aa3b, v235
	v_exp_f32_e32 v228, v228
	v_exp_f32_e32 v229, v229
	v_exp_f32_e32 v230, v230
	v_exp_f32_e32 v231, v231
	v_exp_f32_e32 v232, v232
	v_exp_f32_e32 v233, v233
	v_exp_f32_e32 v234, v234
	v_exp_f32_e32 v235, v235
	s_nop 0
	v_add_f32_e32 v228, 1.0, v228
	v_add_f32_e32 v229, 1.0, v229
	v_add_f32_e32 v230, 1.0, v230
	v_add_f32_e32 v231, 1.0, v231
	v_add_f32_e32 v232, 1.0, v232
	v_add_f32_e32 v233, 1.0, v233
	v_add_f32_e32 v234, 1.0, v234
	v_add_f32_e32 v235, 1.0, v235
	v_rcp_f32_e32 v228, v228
	v_rcp_f32_e32 v229, v229
	v_rcp_f32_e32 v230, v230
	v_rcp_f32_e32 v231, v231
	v_rcp_f32_e32 v232, v232
	v_rcp_f32_e32 v233, v233
	v_rcp_f32_e32 v234, v234
	v_rcp_f32_e32 v235, v235
	s_nop 0
	v_mul_f32_e32 v228, 0xbf60028b, v228
	v_mul_f32_e32 v229, 0xbf60028b, v229
	v_mul_f32_e32 v230, 0xbf60028b, v230
	v_mul_f32_e32 v231, 0xbf60028b, v231
	v_exp_f32_e32 v228, v228
	v_exp_f32_e32 v229, v229
	v_exp_f32_e32 v230, v230
	v_exp_f32_e32 v231, v231
	s_waitcnt lgkmcnt(0)
	v_mul_f32_e32 v106, v236, v232
	v_mul_f32_e32 v107, v237, v233
	v_mul_f32_e32 v108, v238, v234
	v_mul_f32_e32 v109, v239, v235
	v_add_f32_e32 v232, -1.0, v232
	v_add_f32_e32 v233, -1.0, v233
	v_add_f32_e32 v234, -1.0, v234
	v_add_f32_e32 v235, -1.0, v235
	v_fma_f32 v232, v232, v190, 1.0
	v_fma_f32 v233, v233, v190, 1.0
	v_fma_f32 v234, v234, v190, 1.0
	v_fma_f32 v235, v235, v190, 1.0
	v_mul_f32_e32 v224, v224, v232
	v_mul_f32_e32 v225, v225, v233
	v_mul_f32_e32 v226, v226, v234
	v_mul_f32_e32 v227, v227, v235
	v_mul_f32_e32 v232, v130, v224
	v_mul_f32_e32 v233, v131, v225
	v_mul_f32_e32 v234, v132, v226
	v_mul_f32_e32 v235, v133, v227
	ds_write_b32 v248, v232 offset:0
	ds_write_b32 v248, v233 offset:1536
	ds_write_b32 v248, v234 offset:3072
	ds_write_b32 v248, v235 offset:4608
	v_mov_b32_e32 v110, v228
	v_mul_f32_e32 v111, v110, v229
	v_mul_f32_e32 v112, v111, v230
	v_mul_f32_e32 v113, v112, v231
	v_lshrrev_b32_e32 v252, 4, v241
	v_lshlrev_b32_e32 v252, 8, v252
	v_and_b32_e32 v114, 15, v241
	s_lshl_b32 s54, s30, 6
	v_lshl_add_u32 v114, v114, 2, s54
	v_add_u32_e32 v252, v252, v114
	ds_write_b32 v252, v113 offset:55808
	ds_read_b32 v116, v114 offset:55808
	ds_read_b32 v117, v114 offset:56064
	ds_read_b32 v118, v114 offset:56320
	s_waitcnt lgkmcnt(0)
; DI float sigmoidf_(float x) { return frcp(1.f + __expf(-x)); }
; DI void scan_item(const Params& p, int l, bool ctx_out, int item, char* smem) {
;     ...
;       const int ch = 16 * w + cl;
; #pragma unroll
;       for (int rr = 0; rr < 4; ++rr) {
;         const int i = 4 * q4 + rr;
;         const float wl = accw[rr] + w0c, al = acca[rr] + a0c;
;         const float sp = __logf(1.f + __expf(-wl));
;         const float dec = __expf(-__expf(-sp - 0.5f));
;         const float av = sigmoidf_(al);
;         const float zk = zs[(i * 3 + 1) * 64 + ch];
;         const float kkn = ops[(i * 4 + 1) * 64 + ch];
;         ops[(i * 4 + 0) * 64 + ch] = dec;
;         ops[(i * 4 + 2) * 64 + ch] = kkn * av;
;         ops[(i * 4 + 3) * 64 + ch] = zk * (1.f + (av - 1.f) * kac);
;       }
;     }
;     if (ci + 1 < NCH) ISSUE_LOADS(ci + 1)
	v_mul_f32_e32 v117, v116, v117
	v_mul_f32_e32 v118, v117, v118
	v_cndmask_b32_e64 v120, 1.0, v116, s[0:1]
	v_cndmask_b32_e64 v120, v120, v117, s[2:3]
	s_mov_b32 vcc_lo, 0
	s_mov_b32 vcc_hi, 0xffff0000
	v_cndmask_b32_e32 v120, v120, v118, vcc
	v_mov_b32_e32 v121, v120
	v_mul_f32_e32 v110, v120, v110
	v_mul_f32_e32 v111, v120, v111
	v_mul_f32_e32 v112, v120, v112
	v_mul_f32_e32 v113, v120, v113
	v_mov_b32_e32 v116, v110
	v_mov_b32_e32 v117, v111
	v_mov_b32_e32 v118, v112
	ds_write_b32 v252, v113 offset:56832
	v_rcp_f32_e32 v228, v110
	v_rcp_f32_e32 v229, v111
	v_rcp_f32_e32 v230, v112
	v_rcp_f32_e32 v231, v113
	v_mul_f32_e32 v236, v236, v121
	v_mul_f32_e32 v237, v237, v116
	v_mul_f32_e32 v238, v238, v117
	v_mul_f32_e32 v239, v239, v118
	s_cmp_eq_u32 s27, 1
	s_cselect_b64 vcc, -1, 0
	v_cndmask_b32_e32 v121, v110, v121, vcc
	v_cndmask_b32_e32 v116, v111, v116, vcc
	v_cndmask_b32_e32 v117, v112, v117, vcc
	v_cndmask_b32_e32 v118, v113, v118, vcc
	v_mul_f32_e32 v130, v130, v121
	v_mul_f32_e32 v131, v131, v116
	v_mul_f32_e32 v132, v132, v117
	v_mul_f32_e32 v133, v133, v118
	v_mul_f32_e32 v106, v106, v228
	v_mul_f32_e32 v107, v107, v229
	v_mul_f32_e32 v108, v108, v230
	v_mul_f32_e32 v109, v109, v231
	v_mul_f32_e32 v224, v224, v228
	v_mul_f32_e32 v225, v225, v229
	v_mul_f32_e32 v226, v226, v230
	v_mul_f32_e32 v227, v227, v231
	ds_write_b32 v248, v236 offset:256
	ds_write_b32 v248, v130 offset:1024
	ds_write_b32 v248, v106 offset:512
	ds_write_b32 v248, v224 offset:768
	ds_write_b32 v248, v237 offset:1792
	ds_write_b32 v248, v131 offset:2560
	ds_write_b32 v248, v107 offset:2048
	ds_write_b32 v248, v225 offset:2304
	ds_write_b32 v248, v238 offset:3328
	ds_write_b32 v248, v132 offset:4096
	ds_write_b32 v248, v108 offset:3584
	ds_write_b32 v248, v226 offset:3840
	ds_write_b32 v248, v239 offset:4864
	ds_write_b32 v248, v133 offset:5632
	ds_write_b32 v248, v109 offset:5120
	ds_write_b32 v248, v227 offset:5376
	s_add_i32 s62, s31, 1
	s_cmp_lt_u32 s62, 144
	s_cbranch_scc0 .Lscan_noload
	s_lshl_b32 s54, s29, 8
	s_add_i32 s54, s54, 32768
	s_lshl_b32 s55, s29, 11
	s_lshl_b32 s56, s62, 4
	s_add_i32 s57, s56, -256
	s_movk_i32 s58, 256
	s_movk_i32 s59, 2048
	s_cmp_lt_u32 s62, 16
	s_cselect_b32 s72, s58, s59
	s_cselect_b32 s75, 1, 0
	s_cselect_b32 s73, s54, s55
	s_cselect_b32 s74, s56, s57
	s_cmp_eq_u32 s75, 1
	s_cselect_b64 vcc, -1, 0
	v_cndmask_b32_e32 v252, v213, v214, vcc
	v_add_u32_e32 v211, v209, v252
	v_add_u32_e32 v212, v210, v252
	s_lshl_b32 s54, s30, 2
	s_add_i32 s54, s54, s74
	s_sub_i32 s55, s72, s54
	s_add_i32 s55, s55, -1
	s_cmp_eq_u32 s27, 1
	s_cselect_b32 s54, s55, s54
	s_add_i32 s55, s54, s73
	s_mul_i32 s55, s55, 3840
	s_add_u32 s64, s32, s55
	s_addc_u32 s65, s33, 0
	s_add_u32 s66, s34, s55
	s_addc_u32 s67, s35, 0
	s_and_b32 s56, s54, 63
	s_lshr_b32 s57, s54, 6
	s_cmp_eq_u32 s75, 1
	s_cselect_b32 s56, s54, s56
	s_cselect_b32 s58, 255, 63
	s_cselect_b32 s59, s54, s57
	s_cselect_b32 s60, 255, 31
	s_cselect_b32 s61, s54, s57
	s_cselect_b32 s57, s54, s56
	s_cmp_gt_u32 s56, 0
	s_cselect_b64 s[68:69], s[40:41], 0
	s_cmp_lt_u32 s57, s58
	s_cselect_b64 s[54:55], s[42:43], 0
	s_or_b64 s[68:69], s[68:69], s[54:55]
	s_cmp_gt_u32 s59, 0
	s_cselect_b64 s[54:55], s[44:45], 0
	s_or_b64 s[68:69], s[68:69], s[54:55]
	s_cmp_lt_u32 s61, s60
	s_cselect_b64 s[54:55], s[46:47], 0
	s_or_b64 s[68:69], s[68:69], s[54:55]
	v_mov_b32_e32 v131, 0
	v_mov_b32_e32 v133, 0
	v_mov_b32_e32 v135, 0
	v_mov_b32_e32 v137, 0
	v_mov_b32_e32 v139, 0
	global_load_ushort v130, v209, s[64:65]
	global_load_ushort v132, v209, s[64:65] offset:1024
	global_load_ushort v134, v209, s[64:65] offset:2048
	global_load_ushort v136, v210, s[64:65]
	global_load_ushort v138, v210, s[64:65] offset:256
	s_mov_b64 exec, s[68:69]
	global_load_ushort v131, v211, s[66:67]
	global_load_ushort v133, v211, s[66:67] offset:1024
	global_load_ushort v135, v211, s[66:67] offset:2048
	global_load_ushort v137, v212, s[66:67]
	global_load_ushort v139, v212, s[66:67] offset:256
	s_mov_b64 exec, -1
	s_lshl_b32 s54, s30, 2
	s_add_i32 s54, s54, s74
	s_add_i32 s54, s54, 1
	s_sub_i32 s55, s72, s54
	s_add_i32 s55, s55, -1
	s_cmp_eq_u32 s27, 1
	s_cselect_b32 s54, s55, s54
	s_add_i32 s55, s54, s73
	s_mul_i32 s55, s55, 3840
	s_add_u32 s64, s32, s55
	s_addc_u32 s65, s33, 0
	s_add_u32 s66, s34, s55
	s_addc_u32 s67, s35, 0
	s_and_b32 s56, s54, 63
	s_lshr_b32 s57, s54, 6
	s_cmp_eq_u32 s75, 1
	s_cselect_b32 s56, s54, s56
	s_cselect_b32 s58, 255, 63
	s_cselect_b32 s59, s54, s57
	s_cselect_b32 s60, 255, 31
	s_cselect_b32 s61, s54, s57
	s_cselect_b32 s57, s54, s56
	s_cmp_gt_u32 s56, 0
	s_cselect_b64 s[68:69], s[40:41], 0
	s_cmp_lt_u32 s57, s58
	s_cselect_b64 s[54:55], s[42:43], 0
	s_or_b64 s[68:69], s[68:69], s[54:55]
	s_cmp_gt_u32 s59, 0
	s_cselect_b64 s[54:55], s[44:45], 0
	s_or_b64 s[68:69], s[68:69], s[54:55]
	s_cmp_lt_u32 s61, s60
	s_cselect_b64 s[54:55], s[46:47], 0
	s_or_b64 s[68:69], s[68:69], s[54:55]
	v_mov_b32_e32 v141, 0
	v_mov_b32_e32 v143, 0
	v_mov_b32_e32 v145, 0
	v_mov_b32_e32 v147, 0
	v_mov_b32_e32 v149, 0
	global_load_ushort v140, v209, s[64:65]
	global_load_ushort v142, v209, s[64:65] offset:1024
	global_load_ushort v144, v209, s[64:65] offset:2048
	global_load_ushort v146, v210, s[64:65]
	global_load_ushort v148, v210, s[64:65] offset:256
	s_mov_b64 exec, s[68:69]
	global_load_ushort v141, v211, s[66:67]
	global_load_ushort v143, v211, s[66:67] offset:1024
	global_load_ushort v145, v211, s[66:67] offset:2048
	global_load_ushort v147, v212, s[66:67]
	global_load_ushort v149, v212, s[66:67] offset:256
	s_mov_b64 exec, -1
	s_lshl_b32 s54, s30, 2
	s_add_i32 s54, s54, s74
	s_add_i32 s54, s54, 2
	s_sub_i32 s55, s72, s54
; DI void scan_item(const Params& p, int l, bool ctx_out, int item, char* smem) {
;     ...
;     if (ci + 1 < NCH) ISSUE_LOADS(ci + 1)
	s_add_i32 s55, s55, -1
	s_cmp_eq_u32 s27, 1
	s_cselect_b32 s54, s55, s54
	s_add_i32 s55, s54, s73
	s_mul_i32 s55, s55, 3840
	s_add_u32 s64, s32, s55
	s_addc_u32 s65, s33, 0
	s_add_u32 s66, s34, s55
	s_addc_u32 s67, s35, 0
	s_and_b32 s56, s54, 63
	s_lshr_b32 s57, s54, 6
	s_cmp_eq_u32 s75, 1
	s_cselect_b32 s56, s54, s56
	s_cselect_b32 s58, 255, 63
	s_cselect_b32 s59, s54, s57
	s_cselect_b32 s60, 255, 31
	s_cselect_b32 s61, s54, s57
	s_cselect_b32 s57, s54, s56
	s_cmp_gt_u32 s56, 0
	s_cselect_b64 s[68:69], s[40:41], 0
	s_cmp_lt_u32 s57, s58
	s_cselect_b64 s[54:55], s[42:43], 0
	s_or_b64 s[68:69], s[68:69], s[54:55]
	s_cmp_gt_u32 s59, 0
	s_cselect_b64 s[54:55], s[44:45], 0
	s_or_b64 s[68:69], s[68:69], s[54:55]
	s_cmp_lt_u32 s61, s60
	s_cselect_b64 s[54:55], s[46:47], 0
	s_or_b64 s[68:69], s[68:69], s[54:55]
	v_mov_b32_e32 v151, 0
	v_mov_b32_e32 v153, 0
	v_mov_b32_e32 v155, 0
	v_mov_b32_e32 v157, 0
	v_mov_b32_e32 v159, 0
	global_load_ushort v150, v209, s[64:65]
	global_load_ushort v152, v209, s[64:65] offset:1024
	global_load_ushort v154, v209, s[64:65] offset:2048
	global_load_ushort v156, v210, s[64:65]
	global_load_ushort v158, v210, s[64:65] offset:256
	s_mov_b64 exec, s[68:69]
	global_load_ushort v151, v211, s[66:67]
	global_load_ushort v153, v211, s[66:67] offset:1024
	global_load_ushort v155, v211, s[66:67] offset:2048
	global_load_ushort v157, v212, s[66:67]
	global_load_ushort v159, v212, s[66:67] offset:256
	s_mov_b64 exec, -1
	s_lshl_b32 s54, s30, 2
	s_add_i32 s54, s54, s74
	s_add_i32 s54, s54, 3
	s_sub_i32 s55, s72, s54
	s_add_i32 s55, s55, -1
	s_cmp_eq_u32 s27, 1
	s_cselect_b32 s54, s55, s54
	s_add_i32 s55, s54, s73
	s_mul_i32 s55, s55, 3840
	s_add_u32 s64, s32, s55
	s_addc_u32 s65, s33, 0
	s_add_u32 s66, s34, s55
	s_addc_u32 s67, s35, 0
	s_and_b32 s56, s54, 63
	s_lshr_b32 s57, s54, 6
	s_cmp_eq_u32 s75, 1
	s_cselect_b32 s56, s54, s56
	s_cselect_b32 s58, 255, 63
	s_cselect_b32 s59, s54, s57
	s_cselect_b32 s60, 255, 31
	s_cselect_b32 s61, s54, s57
	s_cselect_b32 s57, s54, s56
	s_cmp_gt_u32 s56, 0
	s_cselect_b64 s[68:69], s[40:41], 0
	s_cmp_lt_u32 s57, s58
	s_cselect_b64 s[54:55], s[42:43], 0
	s_or_b64 s[68:69], s[68:69], s[54:55]
	s_cmp_gt_u32 s59, 0
	s_cselect_b64 s[54:55], s[44:45], 0
	s_or_b64 s[68:69], s[68:69], s[54:55]
	s_cmp_lt_u32 s61, s60
	s_cselect_b64 s[54:55], s[46:47], 0
	s_or_b64 s[68:69], s[68:69], s[54:55]
	v_mov_b32_e32 v161, 0
	v_mov_b32_e32 v163, 0
	v_mov_b32_e32 v165, 0
	v_mov_b32_e32 v167, 0
	v_mov_b32_e32 v169, 0
	global_load_ushort v160, v209, s[64:65]
	global_load_ushort v162, v209, s[64:65] offset:1024
	global_load_ushort v164, v209, s[64:65] offset:2048
	global_load_ushort v166, v210, s[64:65]
	global_load_ushort v168, v210, s[64:65] offset:256
	s_mov_b64 exec, s[68:69]
	global_load_ushort v161, v211, s[66:67]
	global_load_ushort v163, v211, s[66:67] offset:1024
	global_load_ushort v165, v211, s[66:67] offset:2048
	global_load_ushort v167, v212, s[66:67]
	global_load_ushort v169, v212, s[66:67] offset:256
	s_mov_b64 exec, -1
; DI unsigned pack2(float a, float b) { f32x2_t v = {a, b}; bf16x2_t r = __builtin_convertvector(v, bf16x2_t); return __builtin_bit_cast(unsigned, r); }
; DI void scan_item(const Params& p, int l, bool ctx_out, int item, char* smem) {
;     ...
;     __syncthreads();
;     f32x4 nw4 = *(const f32x4*)(ops + 0 * 64 + 4 * kg);
;     f32x4 nkk4 = *(const f32x4*)(ops + 1 * 64 + 4 * kg);
;     f32x4 nb4 = *(const f32x4*)(ops + 2 * 64 + 4 * kg);
;     f32x4 nk4 = *(const f32x4*)(ops + 3 * 64 + 4 * kg);
;     f32x4 nr4 = *(const f32x4*)(zs + 0 * 64 + 4 * kg);
;     f32x4 nv4 = *(const f32x4*)(zs + 2 * 64 + 16 * w + 4 * rg);
;     ...
;       if (emit) {
;         float bo = r4[0] * k4[0] * rk4[0] + r4[1] * k4[1] * rk4[1] + r4[2] * k4[2] * rk4[2] + r4[3] * k4[3] * rk4[3];
;         bo = allred16(bo);
; #pragma unroll
;         for (int a = 0; a < 4; ++a) y[a] = allred16(y[a]);
;         if (kg == 0) {
;           const int sidx = c0 + i;
;           const int row = rbase + (dir == 0 ? sidx : n - 1 - sidx);
;           *(u32x2*)(YD + (size_t)row * 512 + h * 64 + 16 * w + 4 * rg) = mk2(pack2(y[0], y[1]), pack2(y[2], y[3]));
;           if (tid == 0) BON[(size_t)row * 8 + h] = bo;
.Lscan_noload:
	s_waitcnt lgkmcnt(0)
	s_barrier
	v_add_u32_e32 v249, s77, v219
	v_add_u32_e32 v250, s77, v220
	v_mov_b32_e32 v251, v221
	ds_read_b128 v[30:33], v249 offset:256
	ds_read_b128 v[34:37], v249 offset:272
	ds_read_b128 v[46:49], v249 offset:768
	ds_read_b128 v[50:53], v249 offset:784
	ds_read_b128 v[54:57], v249 offset:1024
	ds_read_b128 v[58:61], v249 offset:1040
	ds_read_b128 v[38:41], v249 offset:512
	ds_read_b128 v[42:45], v249 offset:528
	ds_read_b64 v[62:63], v250 offset:0
	s_sub_i32 s54, s48, s50
	s_add_i32 s54, s54, -1
	s_cmp_eq_u32 s27, 1
	s_cselect_b32 s54, s54, s50
	s_cselect_b32 s71, -1, 1
	s_add_i32 s70, s54, s49
	s_cmp_eq_u32 s51, 1
	s_cbranch_scc0 .Lscan_nobonus
	v_add_u32_e32 v248, s77, v215
	ds_read_b32 v224, v248 offset:0
	ds_read_b32 v225, v248 offset:1536
	ds_read_b32 v226, v248 offset:3072
	ds_read_b32 v227, v248 offset:4608
	s_waitcnt lgkmcnt(0)
	v_mul_f32_e32 v224, v224, v192
	v_mul_f32_e32 v225, v225, v192
	v_mul_f32_e32 v226, v226, v192
	v_mul_f32_e32 v227, v227, v192
	s_nop 0
	v_add_f32_dpp v224, v224, v224 quad_perm:[1,0,3,2] row_mask:0xf bank_mask:0xf bound_ctrl:1
	v_add_f32_dpp v225, v225, v225 quad_perm:[1,0,3,2] row_mask:0xf bank_mask:0xf bound_ctrl:1
	v_add_f32_dpp v226, v226, v226 quad_perm:[1,0,3,2] row_mask:0xf bank_mask:0xf bound_ctrl:1
	v_add_f32_dpp v227, v227, v227 quad_perm:[1,0,3,2] row_mask:0xf bank_mask:0xf bound_ctrl:1
	v_add_f32_dpp v224, v224, v224 quad_perm:[2,3,0,1] row_mask:0xf bank_mask:0xf bound_ctrl:1
	v_add_f32_dpp v225, v225, v225 quad_perm:[2,3,0,1] row_mask:0xf bank_mask:0xf bound_ctrl:1
	v_add_f32_dpp v226, v226, v226 quad_perm:[2,3,0,1] row_mask:0xf bank_mask:0xf bound_ctrl:1
	v_add_f32_dpp v227, v227, v227 quad_perm:[2,3,0,1] row_mask:0xf bank_mask:0xf bound_ctrl:1
	v_add_f32_dpp v224, v224, v224 row_half_mirror row_mask:0xf bank_mask:0xf bound_ctrl:1
	v_add_f32_dpp v225, v225, v225 row_half_mirror row_mask:0xf bank_mask:0xf bound_ctrl:1
	v_add_f32_dpp v226, v226, v226 row_half_mirror row_mask:0xf bank_mask:0xf bound_ctrl:1
	v_add_f32_dpp v227, v227, v227 row_half_mirror row_mask:0xf bank_mask:0xf bound_ctrl:1
	v_add_f32_dpp v224, v224, v224 row_mirror row_mask:0xf bank_mask:0xf bound_ctrl:1
	v_add_f32_dpp v225, v225, v225 row_mirror row_mask:0xf bank_mask:0xf bound_ctrl:1
	v_add_f32_dpp v226, v226, v226 row_mirror row_mask:0xf bank_mask:0xf bound_ctrl:1
	v_add_f32_dpp v227, v227, v227 row_mirror row_mask:0xf bank_mask:0xf bound_ctrl:1
	s_nop 0
	v_readlane_b32 s54, v224, 0
	v_readlane_b32 s55, v224, 16
	v_readlane_b32 s56, v224, 32
	v_readlane_b32 s57, v224, 48
	s_nop 1
	v_mov_b32_e32 v224, s54
	v_add_f32_e32 v224, s55, v224
	v_add_f32_e32 v224, s56, v224
	v_add_f32_e32 v224, s57, v224
	v_readlane_b32 s54, v225, 0
	v_readlane_b32 s55, v225, 16
	v_readlane_b32 s56, v225, 32
	v_readlane_b32 s57, v225, 48
	s_nop 1
	v_mov_b32_e32 v225, s54
	v_add_f32_e32 v225, s55, v225
	v_add_f32_e32 v225, s56, v225
	v_add_f32_e32 v225, s57, v225
	v_readlane_b32 s54, v226, 0
	v_readlane_b32 s55, v226, 16
	v_readlane_b32 s56, v226, 32
	v_readlane_b32 s57, v226, 48
	s_nop 1
	v_mov_b32_e32 v226, s54
	v_add_f32_e32 v226, s55, v226
	v_add_f32_e32 v226, s56, v226
	v_add_f32_e32 v226, s57, v226
	v_readlane_b32 s54, v227, 0
	v_readlane_b32 s55, v227, 16
	v_readlane_b32 s56, v227, 32
	v_readlane_b32 s57, v227, 48
	s_nop 1
	v_mov_b32_e32 v227, s54
	v_add_f32_e32 v227, s55, v227
	v_add_f32_e32 v227, s56, v227
	v_add_f32_e32 v227, s57, v227
	s_mov_b64 exec, 1
	s_lshl_b32 s54, s30, 2
	s_mul_i32 s54, s54, s71
	s_add_i32 s54, s54, s70
	s_lshl_b32 s54, s54, 5
	s_add_u32 s56, s38, s54
	s_addc_u32 s57, s39, 0
	global_store_dword v240, v224, s[56:57]
	s_lshl_b32 s54, s30, 2
	s_add_i32 s54, s54, 1
	s_mul_i32 s54, s54, s71
	s_add_i32 s54, s54, s70
	s_lshl_b32 s54, s54, 5
	s_add_u32 s56, s38, s54
	s_addc_u32 s57, s39, 0
	global_store_dword v240, v225, s[56:57]
	s_lshl_b32 s54, s30, 2
	s_add_i32 s54, s54, 2
	s_mul_i32 s54, s54, s71
	s_add_i32 s54, s54, s70
	s_lshl_b32 s54, s54, 5
	s_add_u32 s56, s38, s54
	s_addc_u32 s57, s39, 0
	global_store_dword v240, v226, s[56:57]
	s_lshl_b32 s54, s30, 2
	s_add_i32 s54, s54, 3
	s_mul_i32 s54, s54, s71
	s_add_i32 s54, s54, s70
	s_lshl_b32 s54, s54, 5
	s_add_u32 s56, s38, s54
	s_addc_u32 s57, s39, 0
	global_store_dword v240, v227, s[56:57]
	s_mov_b64 exec, -1

; DI void scan_item(const Params& p, int l, bool ctx_out, int item, char* smem) {
;     ...
; #pragma unroll 2
;     for (int i = 0; i < TC; ++i) {
;       const f32x4 w4 = nw4, kk4 = nkk4, b4 = nb4, k4 = nk4, r4 = nr4, v4 = nv4;
;       if (i + 1 < TC) {
;         const int i1 = i + 1;
;         nw4 = *(const f32x4*)(ops + (i1 * 4 + 0) * 64 + 4 * kg);
;         nkk4 = *(const f32x4*)(ops + (i1 * 4 + 1) * 64 + 4 * kg);
;         nb4 = *(const f32x4*)(ops + (i1 * 4 + 2) * 64 + 4 * kg);
;         nk4 = *(const f32x4*)(ops + (i1 * 4 + 3) * 64 + 4 * kg);
;         nr4 = *(const f32x4*)(zs + (i1 * 3 + 0) * 64 + 4 * kg);
;         nv4 = *(const f32x4*)(zs + (i1 * 3 + 2) * 64 + 16 * w + 4 * rg);
;       }
;       float sk[4], y[4];
; #pragma unroll
;       for (int a = 0; a < 4; ++a) {
;         sk[a] = S[a][0] * kk4[0] + S[a][1] * kk4[1] + S[a][2] * kk4[2] + S[a][3] * kk4[3];
;         if (dir == 1) y[a] = S[a][0] * r4[0] + S[a][1] * r4[1] + S[a][2] * r4[2] + S[a][3] * r4[3];
;       }
; #pragma unroll
;       for (int a = 0; a < 4; ++a) sk[a] = allred16(sk[a]);
; #pragma unroll
;       for (int a = 0; a < 4; ++a)
; #pragma unroll
;         for (int j = 0; j < 4; ++j) S[a][j] = S[a][j] * w4[j] + (v4[a] * k4[j] - sk[a] * b4[j]);
;       if (dir == 0) {
; #pragma unroll
;         for (int a = 0; a < 4; ++a) y[a] = S[a][0] * r4[0] + S[a][1] * r4[1] + S[a][2] * r4[2] + S[a][3] * r4[3];
;       }
.Lscan_step_loop0:
	ds_read_b128 v[72:75], v249 offset:1792
	ds_read_b128 v[76:79], v249 offset:1808
	ds_read_b128 v[88:91], v249 offset:2304
	ds_read_b128 v[92:95], v249 offset:2320
	ds_read_b128 v[96:99], v249 offset:2560
	ds_read_b128 v[100:103], v249 offset:2576
	ds_read_b128 v[80:83], v249 offset:2048
	ds_read_b128 v[84:87], v249 offset:2064
	ds_read_b64 v[104:105], v250 offset:1536
	s_waitcnt lgkmcnt(9)
	v_pk_mul_f32 v[122:123], v[6:7], v[30:31] op_sel_hi:[1,0]
	v_pk_mul_f32 v[126:127], v[8:9], v[30:31] op_sel:[0,1] op_sel_hi:[1,1]
	v_pk_fma_f32 v[122:123], v[10:11], v[32:33], v[122:123] op_sel_hi:[1,0,1]
	v_pk_fma_f32 v[126:127], v[12:13], v[32:33], v[126:127] op_sel:[0,1,0] op_sel_hi:[1,1,1]
	v_pk_fma_f32 v[122:123], v[14:15], v[34:35], v[122:123] op_sel_hi:[1,0,1]
	v_pk_fma_f32 v[126:127], v[16:17], v[34:35], v[126:127] op_sel:[0,1,0] op_sel_hi:[1,1,1]
	v_pk_fma_f32 v[122:123], v[18:19], v[36:37], v[122:123] op_sel_hi:[1,0,1]
	v_pk_fma_f32 v[126:127], v[20:21], v[36:37], v[126:127] op_sel:[0,1,0] op_sel_hi:[1,1,1]
	v_pk_add_f32 v[122:123], v[122:123], v[126:127]
	v_pk_fma_f32 v[6:7], v[62:63], v[46:47], v[6:7] op_sel_hi:[1,0,1]
	v_pk_fma_f32 v[8:9], v[62:63], v[46:47], v[8:9] op_sel:[0,1,0] op_sel_hi:[1,1,1]
	v_add_f32_dpp v122, v122, v122 quad_perm:[1,0,3,2] row_mask:0xf bank_mask:0xf bound_ctrl:1
	v_add_f32_dpp v123, v123, v123 quad_perm:[1,0,3,2] row_mask:0xf bank_mask:0xf bound_ctrl:1
	v_pk_fma_f32 v[10:11], v[62:63], v[48:49], v[10:11] op_sel_hi:[1,0,1]
	v_add_f32_dpp v122, v122, v122 quad_perm:[2,3,0,1] row_mask:0xf bank_mask:0xf bound_ctrl:1
	v_add_f32_dpp v123, v123, v123 quad_perm:[2,3,0,1] row_mask:0xf bank_mask:0xf bound_ctrl:1
	v_pk_fma_f32 v[12:13], v[62:63], v[48:49], v[12:13] op_sel:[0,1,0] op_sel_hi:[1,1,1]
	v_add_f32_dpp v122, v122, v122 row_half_mirror row_mask:0xf bank_mask:0xf bound_ctrl:1
	v_add_f32_dpp v123, v123, v123 row_half_mirror row_mask:0xf bank_mask:0xf bound_ctrl:1
	v_pk_fma_f32 v[14:15], v[62:63], v[50:51], v[14:15] op_sel_hi:[1,0,1]
	v_pk_fma_f32 v[16:17], v[62:63], v[50:51], v[16:17] op_sel:[0,1,0] op_sel_hi:[1,1,1]
	v_pk_fma_f32 v[18:19], v[62:63], v[52:53], v[18:19] op_sel_hi:[1,0,1]
	v_pk_fma_f32 v[20:21], v[62:63], v[52:53], v[20:21] op_sel:[0,1,0] op_sel_hi:[1,1,1]
	v_pk_fma_f32 v[6:7], v[122:123], v[38:39], v[6:7] op_sel_hi:[1,0,1] neg_lo:[1,0,0] neg_hi:[1,0,0]
	v_pk_fma_f32 v[8:9], v[122:123], v[38:39], v[8:9] op_sel:[0,1,0] op_sel_hi:[1,1,1] neg_lo:[1,0,0] neg_hi:[1,0,0]
	v_pk_mul_f32 v[124:125], v[6:7], v[54:55] op_sel_hi:[1,0]
	v_pk_fma_f32 v[10:11], v[122:123], v[40:41], v[10:11] op_sel_hi:[1,0,1] neg_lo:[1,0,0] neg_hi:[1,0,0]
	v_pk_mul_f32 v[128:129], v[8:9], v[54:55] op_sel:[0,1] op_sel_hi:[1,1]
	v_pk_fma_f32 v[12:13], v[122:123], v[40:41], v[12:13] op_sel:[0,1,0] op_sel_hi:[1,1,1] neg_lo:[1,0,0] neg_hi:[1,0,0]
	v_pk_fma_f32 v[124:125], v[10:11], v[56:57], v[124:125] op_sel_hi:[1,0,1]
	v_pk_fma_f32 v[14:15], v[122:123], v[42:43], v[14:15] op_sel_hi:[1,0,1] neg_lo:[1,0,0] neg_hi:[1,0,0]
	v_pk_fma_f32 v[128:129], v[12:13], v[56:57], v[128:129] op_sel:[0,1,0] op_sel_hi:[1,1,1]
	v_pk_fma_f32 v[16:17], v[122:123], v[42:43], v[16:17] op_sel:[0,1,0] op_sel_hi:[1,1,1] neg_lo:[1,0,0] neg_hi:[1,0,0]
	v_pk_fma_f32 v[124:125], v[14:15], v[58:59], v[124:125] op_sel_hi:[1,0,1]
	v_pk_fma_f32 v[18:19], v[122:123], v[44:45], v[18:19] op_sel_hi:[1,0,1] neg_lo:[1,0,0] neg_hi:[1,0,0]
	v_pk_fma_f32 v[128:129], v[16:17], v[58:59], v[128:129] op_sel:[0,1,0] op_sel_hi:[1,1,1]
	v_pk_fma_f32 v[20:21], v[122:123], v[44:45], v[20:21] op_sel:[0,1,0] op_sel_hi:[1,1,1] neg_lo:[1,0,0] neg_hi:[1,0,0]
	v_pk_fma_f32 v[124:125], v[18:19], v[60:61], v[124:125] op_sel_hi:[1,0,1]
	v_pk_fma_f32 v[128:129], v[20:21], v[60:61], v[128:129] op_sel:[0,1,0] op_sel_hi:[1,1,1]
	v_pk_add_f32 v[124:125], v[124:125], v[128:129]
	s_nop 1
	v_add_f32_dpp v124, v124, v124 quad_perm:[1,0,3,2] row_mask:0xf bank_mask:0xf bound_ctrl:1
	v_add_f32_dpp v125, v125, v125 quad_perm:[1,0,3,2] row_mask:0xf bank_mask:0xf bound_ctrl:1
	s_nop 0
	v_add_f32_dpp v124, v124, v124 quad_perm:[2,3,0,1] row_mask:0xf bank_mask:0xf bound_ctrl:1
	v_add_f32_dpp v125, v125, v125 quad_perm:[2,3,0,1] row_mask:0xf bank_mask:0xf bound_ctrl:1
	s_nop 0
	v_add_f32_dpp v124, v124, v124 row_half_mirror row_mask:0xf bank_mask:0xf bound_ctrl:1
	v_add_f32_dpp v125, v125, v125 row_half_mirror row_mask:0xf bank_mask:0xf bound_ctrl:1
	v_cvt_pk_bf16_f32 v247, v124, v125
	ds_write_b32 v251, v247 offset:0
	ds_read_b128 v[30:33], v249 offset:3328
	ds_read_b128 v[34:37], v249 offset:3344
	ds_read_b128 v[46:49], v249 offset:3840
	ds_read_b128 v[50:53], v249 offset:3856
	ds_read_b128 v[54:57], v249 offset:4096
	ds_read_b128 v[58:61], v249 offset:4112
	ds_read_b128 v[38:41], v249 offset:3584
	ds_read_b128 v[42:45], v249 offset:3600
	ds_read_b64 v[62:63], v250 offset:3072
	s_waitcnt lgkmcnt(9)
; DI unsigned pack2(float a, float b) { f32x2_t v = {a, b}; bf16x2_t r = __builtin_convertvector(v, bf16x2_t); return __builtin_bit_cast(unsigned, r); }
; DI void scan_item(const Params& p, int l, bool ctx_out, int item, char* smem) {
;     ...
; #pragma unroll 2
;     for (int i = 0; i < TC; ++i) {
;       const f32x4 w4 = nw4, kk4 = nkk4, b4 = nb4, k4 = nk4, r4 = nr4, v4 = nv4;
;       if (i + 1 < TC) {
;         const int i1 = i + 1;
;         nw4 = *(const f32x4*)(ops + (i1 * 4 + 0) * 64 + 4 * kg);
;         nkk4 = *(const f32x4*)(ops + (i1 * 4 + 1) * 64 + 4 * kg);
;         nb4 = *(const f32x4*)(ops + (i1 * 4 + 2) * 64 + 4 * kg);
;         nk4 = *(const f32x4*)(ops + (i1 * 4 + 3) * 64 + 4 * kg);
;         nr4 = *(const f32x4*)(zs + (i1 * 3 + 0) * 64 + 4 * kg);
;         nv4 = *(const f32x4*)(zs + (i1 * 3 + 2) * 64 + 16 * w + 4 * rg);
;       }
;       float sk[4], y[4];
; #pragma unroll
;       for (int a = 0; a < 4; ++a) {
;         sk[a] = S[a][0] * kk4[0] + S[a][1] * kk4[1] + S[a][2] * kk4[2] + S[a][3] * kk4[3];
;         if (dir == 1) y[a] = S[a][0] * r4[0] + S[a][1] * r4[1] + S[a][2] * r4[2] + S[a][3] * r4[3];
;       }
; #pragma unroll
;       for (int a = 0; a < 4; ++a) sk[a] = allred16(sk[a]);
; #pragma unroll
;       for (int a = 0; a < 4; ++a)
; #pragma unroll
;         for (int j = 0; j < 4; ++j) S[a][j] = S[a][j] * w4[j] + (v4[a] * k4[j] - sk[a] * b4[j]);
;       if (dir == 0) {
; #pragma unroll
;         for (int a = 0; a < 4; ++a) y[a] = S[a][0] * r4[0] + S[a][1] * r4[1] + S[a][2] * r4[2] + S[a][3] * r4[3];
;       }
;       if (emit) {
;         float bo = r4[0] * k4[0] * rk4[0] + r4[1] * k4[1] * rk4[1] + r4[2] * k4[2] * rk4[2] + r4[3] * k4[3] * rk4[3];
;         bo = allred16(bo);
; #pragma unroll
;         for (int a = 0; a < 4; ++a) y[a] = allred16(y[a]);
;         if (kg == 0) {
;           const int sidx = c0 + i;
;           const int row = rbase + (dir == 0 ? sidx : n - 1 - sidx);
;           *(u32x2*)(YD + (size_t)row * 512 + h * 64 + 16 * w + 4 * rg) = mk2(pack2(y[0], y[1]), pack2(y[2], y[3]));
;           if (tid == 0) BON[(size_t)row * 8 + h] = bo;
;         }
;       }
;     }
	v_pk_mul_f32 v[122:123], v[6:7], v[72:73] op_sel_hi:[1,0]
	v_pk_mul_f32 v[126:127], v[8:9], v[72:73] op_sel:[0,1] op_sel_hi:[1,1]
	v_pk_fma_f32 v[122:123], v[10:11], v[74:75], v[122:123] op_sel_hi:[1,0,1]
	v_pk_fma_f32 v[126:127], v[12:13], v[74:75], v[126:127] op_sel:[0,1,0] op_sel_hi:[1,1,1]
	v_pk_fma_f32 v[122:123], v[14:15], v[76:77], v[122:123] op_sel_hi:[1,0,1]
	v_pk_fma_f32 v[126:127], v[16:17], v[76:77], v[126:127] op_sel:[0,1,0] op_sel_hi:[1,1,1]
	v_pk_fma_f32 v[122:123], v[18:19], v[78:79], v[122:123] op_sel_hi:[1,0,1]
	v_pk_fma_f32 v[126:127], v[20:21], v[78:79], v[126:127] op_sel:[0,1,0] op_sel_hi:[1,1,1]
	v_pk_add_f32 v[122:123], v[122:123], v[126:127]
	v_pk_fma_f32 v[6:7], v[104:105], v[88:89], v[6:7] op_sel_hi:[1,0,1]
	v_pk_fma_f32 v[8:9], v[104:105], v[88:89], v[8:9] op_sel:[0,1,0] op_sel_hi:[1,1,1]
	v_add_f32_dpp v122, v122, v122 quad_perm:[1,0,3,2] row_mask:0xf bank_mask:0xf bound_ctrl:1
	v_add_f32_dpp v123, v123, v123 quad_perm:[1,0,3,2] row_mask:0xf bank_mask:0xf bound_ctrl:1
	v_pk_fma_f32 v[10:11], v[104:105], v[90:91], v[10:11] op_sel_hi:[1,0,1]
	v_add_f32_dpp v122, v122, v122 quad_perm:[2,3,0,1] row_mask:0xf bank_mask:0xf bound_ctrl:1
	v_add_f32_dpp v123, v123, v123 quad_perm:[2,3,0,1] row_mask:0xf bank_mask:0xf bound_ctrl:1
	v_pk_fma_f32 v[12:13], v[104:105], v[90:91], v[12:13] op_sel:[0,1,0] op_sel_hi:[1,1,1]
	v_add_f32_dpp v122, v122, v122 row_half_mirror row_mask:0xf bank_mask:0xf bound_ctrl:1
	v_add_f32_dpp v123, v123, v123 row_half_mirror row_mask:0xf bank_mask:0xf bound_ctrl:1
	v_pk_fma_f32 v[14:15], v[104:105], v[92:93], v[14:15] op_sel_hi:[1,0,1]
	v_pk_fma_f32 v[16:17], v[104:105], v[92:93], v[16:17] op_sel:[0,1,0] op_sel_hi:[1,1,1]
	v_pk_fma_f32 v[18:19], v[104:105], v[94:95], v[18:19] op_sel_hi:[1,0,1]
	v_pk_fma_f32 v[20:21], v[104:105], v[94:95], v[20:21] op_sel:[0,1,0] op_sel_hi:[1,1,1]
	v_pk_fma_f32 v[6:7], v[122:123], v[80:81], v[6:7] op_sel_hi:[1,0,1] neg_lo:[1,0,0] neg_hi:[1,0,0]
	v_pk_fma_f32 v[8:9], v[122:123], v[80:81], v[8:9] op_sel:[0,1,0] op_sel_hi:[1,1,1] neg_lo:[1,0,0] neg_hi:[1,0,0]
	v_pk_mul_f32 v[124:125], v[6:7], v[96:97] op_sel_hi:[1,0]
	v_pk_fma_f32 v[10:11], v[122:123], v[82:83], v[10:11] op_sel_hi:[1,0,1] neg_lo:[1,0,0] neg_hi:[1,0,0]
	v_pk_mul_f32 v[128:129], v[8:9], v[96:97] op_sel:[0,1] op_sel_hi:[1,1]
	v_pk_fma_f32 v[12:13], v[122:123], v[82:83], v[12:13] op_sel:[0,1,0] op_sel_hi:[1,1,1] neg_lo:[1,0,0] neg_hi:[1,0,0]
	v_pk_fma_f32 v[124:125], v[10:11], v[98:99], v[124:125] op_sel_hi:[1,0,1]
	v_pk_fma_f32 v[14:15], v[122:123], v[84:85], v[14:15] op_sel_hi:[1,0,1] neg_lo:[1,0,0] neg_hi:[1,0,0]
	v_pk_fma_f32 v[128:129], v[12:13], v[98:99], v[128:129] op_sel:[0,1,0] op_sel_hi:[1,1,1]
	v_pk_fma_f32 v[16:17], v[122:123], v[84:85], v[16:17] op_sel:[0,1,0] op_sel_hi:[1,1,1] neg_lo:[1,0,0] neg_hi:[1,0,0]
	v_pk_fma_f32 v[124:125], v[14:15], v[100:101], v[124:125] op_sel_hi:[1,0,1]
	v_pk_fma_f32 v[18:19], v[122:123], v[86:87], v[18:19] op_sel_hi:[1,0,1] neg_lo:[1,0,0] neg_hi:[1,0,0]
	v_pk_fma_f32 v[128:129], v[16:17], v[100:101], v[128:129] op_sel:[0,1,0] op_sel_hi:[1,1,1]
	v_pk_fma_f32 v[20:21], v[122:123], v[86:87], v[20:21] op_sel:[0,1,0] op_sel_hi:[1,1,1] neg_lo:[1,0,0] neg_hi:[1,0,0]
	v_pk_fma_f32 v[124:125], v[18:19], v[102:103], v[124:125] op_sel_hi:[1,0,1]
	v_pk_fma_f32 v[128:129], v[20:21], v[102:103], v[128:129] op_sel:[0,1,0] op_sel_hi:[1,1,1]
	v_pk_add_f32 v[124:125], v[124:125], v[128:129]
	s_nop 1
	v_add_f32_dpp v124, v124, v124 quad_perm:[1,0,3,2] row_mask:0xf bank_mask:0xf bound_ctrl:1
	v_add_f32_dpp v125, v125, v125 quad_perm:[1,0,3,2] row_mask:0xf bank_mask:0xf bound_ctrl:1
	s_nop 0
	v_add_f32_dpp v124, v124, v124 quad_perm:[2,3,0,1] row_mask:0xf bank_mask:0xf bound_ctrl:1
	v_add_f32_dpp v125, v125, v125 quad_perm:[2,3,0,1] row_mask:0xf bank_mask:0xf bound_ctrl:1
	s_nop 0
	v_add_f32_dpp v124, v124, v124 row_half_mirror row_mask:0xf bank_mask:0xf bound_ctrl:1
	v_add_f32_dpp v125, v125, v125 row_half_mirror row_mask:0xf bank_mask:0xf bound_ctrl:1
	v_cvt_pk_bf16_f32 v247, v124, v125
	ds_write_b32 v251, v247 offset:128
	v_add_u32_e32 v249, 3072, v249
	v_add_u32_e32 v250, 3072, v250
	v_add_u32_e32 v251, 256, v251
	s_add_i32 s53, s53, 1
	s_cmp_lt_u32 s53, 8
	s_cbranch_scc1 .Lscan_step_loop0
	s_branch .Lscan_flush

; DI void scan_item(const Params& p, int l, bool ctx_out, int item, char* smem) {
;     ...
;     for (int i = 0; i < TC; ++i) {
;       const f32x4 w4 = nw4, kk4 = nkk4, b4 = nb4, k4 = nk4, r4 = nr4, v4 = nv4;
;       if (i + 1 < TC) {
;         const int i1 = i + 1;
;         nw4 = *(const f32x4*)(ops + (i1 * 4 + 0) * 64 + 4 * kg);
;         nkk4 = *(const f32x4*)(ops + (i1 * 4 + 1) * 64 + 4 * kg);
;         nb4 = *(const f32x4*)(ops + (i1 * 4 + 2) * 64 + 4 * kg);
;         nk4 = *(const f32x4*)(ops + (i1 * 4 + 3) * 64 + 4 * kg);
;         nr4 = *(const f32x4*)(zs + (i1 * 3 + 0) * 64 + 4 * kg);
;         nv4 = *(const f32x4*)(zs + (i1 * 3 + 2) * 64 + 16 * w + 4 * rg);
;       }
;       float sk[4], y[4];
; #pragma unroll
;       for (int a = 0; a < 4; ++a) {
;         sk[a] = S[a][0] * kk4[0] + S[a][1] * kk4[1] + S[a][2] * kk4[2] + S[a][3] * kk4[3];
;         if (dir == 1) y[a] = S[a][0] * r4[0] + S[a][1] * r4[1] + S[a][2] * r4[2] + S[a][3] * r4[3];
;       }
; #pragma unroll
;       for (int a = 0; a < 4; ++a) sk[a] = allred16(sk[a]);
; #pragma unroll
;       for (int a = 0; a < 4; ++a)
; #pragma unroll
;         for (int j = 0; j < 4; ++j) S[a][j] = S[a][j] * w4[j] + (v4[a] * k4[j] - sk[a] * b4[j]);
;       if (dir == 0) {
; #pragma unroll
;         for (int a = 0; a < 4; ++a) y[a] = S[a][0] * r4[0] + S[a][1] * r4[1] + S[a][2] * r4[2] + S[a][3] * r4[3];
;       }
.Lscan_step_loop1:
	ds_read_b128 v[72:75], v249 offset:1792
	ds_read_b128 v[76:79], v249 offset:1808
	ds_read_b128 v[88:91], v249 offset:2304
	ds_read_b128 v[92:95], v249 offset:2320
	ds_read_b128 v[96:99], v249 offset:2560
	ds_read_b128 v[100:103], v249 offset:2576
	ds_read_b128 v[80:83], v249 offset:2048
	ds_read_b128 v[84:87], v249 offset:2064
	ds_read_b64 v[104:105], v250 offset:1536
	s_waitcnt lgkmcnt(9)
	v_pk_mul_f32 v[122:123], v[6:7], v[30:31] op_sel_hi:[1,0]
	v_pk_mul_f32 v[124:125], v[6:7], v[54:55] op_sel_hi:[1,0]
	v_pk_mul_f32 v[126:127], v[8:9], v[30:31] op_sel:[0,1] op_sel_hi:[1,1]
	v_pk_mul_f32 v[128:129], v[8:9], v[54:55] op_sel:[0,1] op_sel_hi:[1,1]
	v_pk_fma_f32 v[122:123], v[10:11], v[32:33], v[122:123] op_sel_hi:[1,0,1]
	v_pk_fma_f32 v[124:125], v[10:11], v[56:57], v[124:125] op_sel_hi:[1,0,1]
	v_pk_fma_f32 v[126:127], v[12:13], v[32:33], v[126:127] op_sel:[0,1,0] op_sel_hi:[1,1,1]
	v_pk_fma_f32 v[128:129], v[12:13], v[56:57], v[128:129] op_sel:[0,1,0] op_sel_hi:[1,1,1]
	v_pk_fma_f32 v[122:123], v[14:15], v[34:35], v[122:123] op_sel_hi:[1,0,1]
	v_pk_fma_f32 v[124:125], v[14:15], v[58:59], v[124:125] op_sel_hi:[1,0,1]
	v_pk_fma_f32 v[126:127], v[16:17], v[34:35], v[126:127] op_sel:[0,1,0] op_sel_hi:[1,1,1]
	v_pk_fma_f32 v[128:129], v[16:17], v[58:59], v[128:129] op_sel:[0,1,0] op_sel_hi:[1,1,1]
	v_pk_fma_f32 v[122:123], v[18:19], v[36:37], v[122:123] op_sel_hi:[1,0,1]
	v_pk_fma_f32 v[124:125], v[18:19], v[60:61], v[124:125] op_sel_hi:[1,0,1]
	v_pk_fma_f32 v[126:127], v[20:21], v[36:37], v[126:127] op_sel:[0,1,0] op_sel_hi:[1,1,1]
	v_pk_fma_f32 v[128:129], v[20:21], v[60:61], v[128:129] op_sel:[0,1,0] op_sel_hi:[1,1,1]
	v_pk_add_f32 v[122:123], v[122:123], v[126:127]
	v_pk_add_f32 v[124:125], v[124:125], v[128:129]
	v_pk_fma_f32 v[6:7], v[62:63], v[46:47], v[6:7] op_sel_hi:[1,0,1]
	v_add_f32_dpp v122, v122, v122 quad_perm:[1,0,3,2] row_mask:0xf bank_mask:0xf bound_ctrl:1
	v_add_f32_dpp v123, v123, v123 quad_perm:[1,0,3,2] row_mask:0xf bank_mask:0xf bound_ctrl:1
	v_add_f32_dpp v124, v124, v124 quad_perm:[1,0,3,2] row_mask:0xf bank_mask:0xf bound_ctrl:1
	v_add_f32_dpp v125, v125, v125 quad_perm:[1,0,3,2] row_mask:0xf bank_mask:0xf bound_ctrl:1
	v_add_f32_dpp v122, v122, v122 quad_perm:[2,3,0,1] row_mask:0xf bank_mask:0xf bound_ctrl:1
	v_add_f32_dpp v123, v123, v123 quad_perm:[2,3,0,1] row_mask:0xf bank_mask:0xf bound_ctrl:1
	v_add_f32_dpp v124, v124, v124 quad_perm:[2,3,0,1] row_mask:0xf bank_mask:0xf bound_ctrl:1
	v_add_f32_dpp v125, v125, v125 quad_perm:[2,3,0,1] row_mask:0xf bank_mask:0xf bound_ctrl:1
	v_add_f32_dpp v122, v122, v122 row_half_mirror row_mask:0xf bank_mask:0xf bound_ctrl:1
	v_add_f32_dpp v123, v123, v123 row_half_mirror row_mask:0xf bank_mask:0xf bound_ctrl:1
	v_add_f32_dpp v124, v124, v124 row_half_mirror row_mask:0xf bank_mask:0xf bound_ctrl:1
	v_add_f32_dpp v125, v125, v125 row_half_mirror row_mask:0xf bank_mask:0xf bound_ctrl:1
	v_pk_fma_f32 v[8:9], v[62:63], v[46:47], v[8:9] op_sel:[0,1,0] op_sel_hi:[1,1,1]
	v_pk_fma_f32 v[10:11], v[62:63], v[48:49], v[10:11] op_sel_hi:[1,0,1]
	v_pk_fma_f32 v[12:13], v[62:63], v[48:49], v[12:13] op_sel:[0,1,0] op_sel_hi:[1,1,1]
	v_pk_fma_f32 v[14:15], v[62:63], v[50:51], v[14:15] op_sel_hi:[1,0,1]
	v_pk_fma_f32 v[16:17], v[62:63], v[50:51], v[16:17] op_sel:[0,1,0] op_sel_hi:[1,1,1]
	v_pk_fma_f32 v[18:19], v[62:63], v[52:53], v[18:19] op_sel_hi:[1,0,1]
	v_pk_fma_f32 v[20:21], v[62:63], v[52:53], v[20:21] op_sel:[0,1,0] op_sel_hi:[1,1,1]
	v_pk_fma_f32 v[6:7], v[122:123], v[38:39], v[6:7] op_sel_hi:[1,0,1] neg_lo:[1,0,0] neg_hi:[1,0,0]
	v_pk_fma_f32 v[8:9], v[122:123], v[38:39], v[8:9] op_sel:[0,1,0] op_sel_hi:[1,1,1] neg_lo:[1,0,0] neg_hi:[1,0,0]
	v_pk_fma_f32 v[10:11], v[122:123], v[40:41], v[10:11] op_sel_hi:[1,0,1] neg_lo:[1,0,0] neg_hi:[1,0,0]
	v_pk_fma_f32 v[12:13], v[122:123], v[40:41], v[12:13] op_sel:[0,1,0] op_sel_hi:[1,1,1] neg_lo:[1,0,0] neg_hi:[1,0,0]
	v_pk_fma_f32 v[14:15], v[122:123], v[42:43], v[14:15] op_sel_hi:[1,0,1] neg_lo:[1,0,0] neg_hi:[1,0,0]
	v_pk_fma_f32 v[16:17], v[122:123], v[42:43], v[16:17] op_sel:[0,1,0] op_sel_hi:[1,1,1] neg_lo:[1,0,0] neg_hi:[1,0,0]
	v_pk_fma_f32 v[18:19], v[122:123], v[44:45], v[18:19] op_sel_hi:[1,0,1] neg_lo:[1,0,0] neg_hi:[1,0,0]
	v_pk_fma_f32 v[20:21], v[122:123], v[44:45], v[20:21] op_sel:[0,1,0] op_sel_hi:[1,1,1] neg_lo:[1,0,0] neg_hi:[1,0,0]
	v_cvt_pk_bf16_f32 v247, v124, v125
	ds_write_b32 v251, v247 offset:0
	ds_read_b128 v[30:33], v249 offset:3328
	ds_read_b128 v[34:37], v249 offset:3344
	ds_read_b128 v[46:49], v249 offset:3840
	ds_read_b128 v[50:53], v249 offset:3856
	ds_read_b128 v[54:57], v249 offset:4096
	ds_read_b128 v[58:61], v249 offset:4112
	ds_read_b128 v[38:41], v249 offset:3584
	ds_read_b128 v[42:45], v249 offset:3600
	ds_read_b64 v[62:63], v250 offset:3072
	s_waitcnt lgkmcnt(9)
; DI unsigned pack2(float a, float b) { f32x2_t v = {a, b}; bf16x2_t r = __builtin_convertvector(v, bf16x2_t); return __builtin_bit_cast(unsigned, r); }
; DI void scan_item(const Params& p, int l, bool ctx_out, int item, char* smem) {
;     ...
;     for (int i = 0; i < TC; ++i) {
;       const f32x4 w4 = nw4, kk4 = nkk4, b4 = nb4, k4 = nk4, r4 = nr4, v4 = nv4;
;       if (i + 1 < TC) {
;         const int i1 = i + 1;
;         nw4 = *(const f32x4*)(ops + (i1 * 4 + 0) * 64 + 4 * kg);
;         nkk4 = *(const f32x4*)(ops + (i1 * 4 + 1) * 64 + 4 * kg);
;         nb4 = *(const f32x4*)(ops + (i1 * 4 + 2) * 64 + 4 * kg);
;         nk4 = *(const f32x4*)(ops + (i1 * 4 + 3) * 64 + 4 * kg);
;         nr4 = *(const f32x4*)(zs + (i1 * 3 + 0) * 64 + 4 * kg);
;         nv4 = *(const f32x4*)(zs + (i1 * 3 + 2) * 64 + 16 * w + 4 * rg);
;       }
;       float sk[4], y[4];
; #pragma unroll
;       for (int a = 0; a < 4; ++a) {
;         sk[a] = S[a][0] * kk4[0] + S[a][1] * kk4[1] + S[a][2] * kk4[2] + S[a][3] * kk4[3];
;         if (dir == 1) y[a] = S[a][0] * r4[0] + S[a][1] * r4[1] + S[a][2] * r4[2] + S[a][3] * r4[3];
;       }
; #pragma unroll
;       for (int a = 0; a < 4; ++a) sk[a] = allred16(sk[a]);
; #pragma unroll
;       for (int a = 0; a < 4; ++a)
; #pragma unroll
;         for (int j = 0; j < 4; ++j) S[a][j] = S[a][j] * w4[j] + (v4[a] * k4[j] - sk[a] * b4[j]);
;       if (dir == 0) {
; #pragma unroll
;         for (int a = 0; a < 4; ++a) y[a] = S[a][0] * r4[0] + S[a][1] * r4[1] + S[a][2] * r4[2] + S[a][3] * r4[3];
;       }
;       if (emit) {
;         float bo = r4[0] * k4[0] * rk4[0] + r4[1] * k4[1] * rk4[1] + r4[2] * k4[2] * rk4[2] + r4[3] * k4[3] * rk4[3];
;         bo = allred16(bo);
; #pragma unroll
;         for (int a = 0; a < 4; ++a) y[a] = allred16(y[a]);
;         if (kg == 0) {
;           const int sidx = c0 + i;
;           const int row = rbase + (dir == 0 ? sidx : n - 1 - sidx);
;           *(u32x2*)(YD + (size_t)row * 512 + h * 64 + 16 * w + 4 * rg) = mk2(pack2(y[0], y[1]), pack2(y[2], y[3]));
;           if (tid == 0) BON[(size_t)row * 8 + h] = bo;
;         }
;       }
;     }
;     __syncthreads();
	v_pk_mul_f32 v[122:123], v[6:7], v[72:73] op_sel_hi:[1,0]
	v_pk_mul_f32 v[124:125], v[6:7], v[96:97] op_sel_hi:[1,0]
	v_pk_mul_f32 v[126:127], v[8:9], v[72:73] op_sel:[0,1] op_sel_hi:[1,1]
	v_pk_mul_f32 v[128:129], v[8:9], v[96:97] op_sel:[0,1] op_sel_hi:[1,1]
	v_pk_fma_f32 v[122:123], v[10:11], v[74:75], v[122:123] op_sel_hi:[1,0,1]
	v_pk_fma_f32 v[124:125], v[10:11], v[98:99], v[124:125] op_sel_hi:[1,0,1]
	v_pk_fma_f32 v[126:127], v[12:13], v[74:75], v[126:127] op_sel:[0,1,0] op_sel_hi:[1,1,1]
	v_pk_fma_f32 v[128:129], v[12:13], v[98:99], v[128:129] op_sel:[0,1,0] op_sel_hi:[1,1,1]
	v_pk_fma_f32 v[122:123], v[14:15], v[76:77], v[122:123] op_sel_hi:[1,0,1]
	v_pk_fma_f32 v[124:125], v[14:15], v[100:101], v[124:125] op_sel_hi:[1,0,1]
	v_pk_fma_f32 v[126:127], v[16:17], v[76:77], v[126:127] op_sel:[0,1,0] op_sel_hi:[1,1,1]
	v_pk_fma_f32 v[128:129], v[16:17], v[100:101], v[128:129] op_sel:[0,1,0] op_sel_hi:[1,1,1]
	v_pk_fma_f32 v[122:123], v[18:19], v[78:79], v[122:123] op_sel_hi:[1,0,1]
	v_pk_fma_f32 v[124:125], v[18:19], v[102:103], v[124:125] op_sel_hi:[1,0,1]
	v_pk_fma_f32 v[126:127], v[20:21], v[78:79], v[126:127] op_sel:[0,1,0] op_sel_hi:[1,1,1]
	v_pk_fma_f32 v[128:129], v[20:21], v[102:103], v[128:129] op_sel:[0,1,0] op_sel_hi:[1,1,1]
	v_pk_add_f32 v[122:123], v[122:123], v[126:127]
	v_pk_add_f32 v[124:125], v[124:125], v[128:129]
	v_pk_fma_f32 v[6:7], v[104:105], v[88:89], v[6:7] op_sel_hi:[1,0,1]
	v_add_f32_dpp v122, v122, v122 quad_perm:[1,0,3,2] row_mask:0xf bank_mask:0xf bound_ctrl:1
	v_add_f32_dpp v123, v123, v123 quad_perm:[1,0,3,2] row_mask:0xf bank_mask:0xf bound_ctrl:1
	v_add_f32_dpp v124, v124, v124 quad_perm:[1,0,3,2] row_mask:0xf bank_mask:0xf bound_ctrl:1
	v_add_f32_dpp v125, v125, v125 quad_perm:[1,0,3,2] row_mask:0xf bank_mask:0xf bound_ctrl:1
	v_add_f32_dpp v122, v122, v122 quad_perm:[2,3,0,1] row_mask:0xf bank_mask:0xf bound_ctrl:1
	v_add_f32_dpp v123, v123, v123 quad_perm:[2,3,0,1] row_mask:0xf bank_mask:0xf bound_ctrl:1
	v_add_f32_dpp v124, v124, v124 quad_perm:[2,3,0,1] row_mask:0xf bank_mask:0xf bound_ctrl:1
	v_add_f32_dpp v125, v125, v125 quad_perm:[2,3,0,1] row_mask:0xf bank_mask:0xf bound_ctrl:1
	v_add_f32_dpp v122, v122, v122 row_half_mirror row_mask:0xf bank_mask:0xf bound_ctrl:1
	v_add_f32_dpp v123, v123, v123 row_half_mirror row_mask:0xf bank_mask:0xf bound_ctrl:1
	v_add_f32_dpp v124, v124, v124 row_half_mirror row_mask:0xf bank_mask:0xf bound_ctrl:1
	v_add_f32_dpp v125, v125, v125 row_half_mirror row_mask:0xf bank_mask:0xf bound_ctrl:1
	v_pk_fma_f32 v[8:9], v[104:105], v[88:89], v[8:9] op_sel:[0,1,0] op_sel_hi:[1,1,1]
	v_pk_fma_f32 v[10:11], v[104:105], v[90:91], v[10:11] op_sel_hi:[1,0,1]
	v_pk_fma_f32 v[12:13], v[104:105], v[90:91], v[12:13] op_sel:[0,1,0] op_sel_hi:[1,1,1]
	v_pk_fma_f32 v[14:15], v[104:105], v[92:93], v[14:15] op_sel_hi:[1,0,1]
	v_pk_fma_f32 v[16:17], v[104:105], v[92:93], v[16:17] op_sel:[0,1,0] op_sel_hi:[1,1,1]
	v_pk_fma_f32 v[18:19], v[104:105], v[94:95], v[18:19] op_sel_hi:[1,0,1]
	v_pk_fma_f32 v[20:21], v[104:105], v[94:95], v[20:21] op_sel:[0,1,0] op_sel_hi:[1,1,1]
	v_pk_fma_f32 v[6:7], v[122:123], v[80:81], v[6:7] op_sel_hi:[1,0,1] neg_lo:[1,0,0] neg_hi:[1,0,0]
	v_pk_fma_f32 v[8:9], v[122:123], v[80:81], v[8:9] op_sel:[0,1,0] op_sel_hi:[1,1,1] neg_lo:[1,0,0] neg_hi:[1,0,0]
	v_pk_fma_f32 v[10:11], v[122:123], v[82:83], v[10:11] op_sel_hi:[1,0,1] neg_lo:[1,0,0] neg_hi:[1,0,0]
	v_pk_fma_f32 v[12:13], v[122:123], v[82:83], v[12:13] op_sel:[0,1,0] op_sel_hi:[1,1,1] neg_lo:[1,0,0] neg_hi:[1,0,0]
	v_pk_fma_f32 v[14:15], v[122:123], v[84:85], v[14:15] op_sel_hi:[1,0,1] neg_lo:[1,0,0] neg_hi:[1,0,0]
	v_pk_fma_f32 v[16:17], v[122:123], v[84:85], v[16:17] op_sel:[0,1,0] op_sel_hi:[1,1,1] neg_lo:[1,0,0] neg_hi:[1,0,0]
	v_pk_fma_f32 v[18:19], v[122:123], v[86:87], v[18:19] op_sel_hi:[1,0,1] neg_lo:[1,0,0] neg_hi:[1,0,0]
	v_pk_fma_f32 v[20:21], v[122:123], v[86:87], v[20:21] op_sel:[0,1,0] op_sel_hi:[1,1,1] neg_lo:[1,0,0] neg_hi:[1,0,0]
	v_cvt_pk_bf16_f32 v247, v124, v125
	ds_write_b32 v251, v247 offset:128
	v_add_u32_e32 v249, 3072, v249
	v_add_u32_e32 v250, 3072, v250
	v_add_u32_e32 v251, 256, v251
	s_add_i32 s53, s53, 1
	s_cmp_lt_u32 s53, 8
	s_cbranch_scc1 .Lscan_step_loop1
.Lscan_flush:
	v_and_b32_e32 v224, 7, v241
	v_lshlrev_b32_e32 v224, 5, v224
	ds_read_b128 v[106:109], v224 offset:57600
	ds_read_b128 v[110:113], v224 offset:57616
	s_waitcnt lgkmcnt(0)
	v_pk_mul_f32 v[6:7], v[6:7], v[106:107] op_sel_hi:[1,0]
	v_pk_mul_f32 v[8:9], v[8:9], v[106:107] op_sel:[0,1] op_sel_hi:[1,1]
	v_pk_mul_f32 v[10:11], v[10:11], v[108:109] op_sel_hi:[1,0]
	v_pk_mul_f32 v[12:13], v[12:13], v[108:109] op_sel:[0,1] op_sel_hi:[1,1]
	v_pk_mul_f32 v[14:15], v[14:15], v[110:111] op_sel_hi:[1,0]
	v_pk_mul_f32 v[16:17], v[16:17], v[110:111] op_sel:[0,1] op_sel_hi:[1,1]
	v_pk_mul_f32 v[18:19], v[18:19], v[112:113] op_sel_hi:[1,0]
	v_pk_mul_f32 v[20:21], v[20:21], v[112:113] op_sel:[0,1] op_sel_hi:[1,1]
	s_cmp_eq_u32 s51, 1
	s_cbranch_scc0 .Lscan_noflush
	s_waitcnt lgkmcnt(0)
	ds_read_b64 v[224:225], v222
	s_mul_i32 s54, s27, 15
	s_sub_i32 s54, s70, s54
	s_lshl_b32 s54, s54, 10
	s_add_u32 s56, s36, s54
	s_addc_u32 s57, s37, 0
	s_waitcnt lgkmcnt(0)
	global_store_dwordx2 v223, v[224:225], s[56:57]
